# GEMM loops: per-segment setprio flips removed, one static setprio 1 for waves 4-7 per GEMM phase
# speedup vs baseline: 1.0099x; 1.0059x over previous
.LBB0_136:
	s_or_b64 exec, exec, s[4:5]
	s_xor_b64 s[0:1], s[0:1], -1
	v_writelane_b32 v253, s0, 28
	s_waitcnt lgkmcnt(0)
	v_mov_b32_e32 v0, v179
	v_writelane_b32 v253, s1, 29
	v_readlane_b32 s0, v250, 51
	v_readlane_b32 s1, v250, 52
	s_barrier
	s_nop 0
	v_cndmask_b32_e64 v1, 0, 1, s[0:1]
	v_cmp_ne_u32_e64 s[4:5], 1, v1
	s_andn2_b64 vcc, exec, s[0:1]
	v_readfirstlane_b32 s0, v0
	v_writelane_b32 v253, s4, 30
	s_nop 1
	v_writelane_b32 v253, s5, 31
	s_cbranch_vccnz .LBB0_152
	v_readfirstlane_b32 s100, v179
	s_lshr_b32 s100, s100, 6
	s_cmp_ge_u32 s100, 4
	s_cbranch_scc0 .Lprio_done0
	s_setprio 1
.Lprio_done0:
	v_lshlrev_b32_e32 v4, 4, v0
	v_add_u32_e32 v2, 0x2000, v4
	v_ashrrev_i32_e32 v1, 31, v2
	v_lshrrev_b32_e32 v1, 22, v1
	v_add_u32_e32 v1, v2, v1
	v_ashrrev_i32_e32 v1, 10, v1
	v_mul_i32_i24_e32 v3, 0x400, v1
	v_sub_u32_e32 v2, v2, v3
	v_lshrrev_b32_e32 v3, 4, v2
	v_bitop3_b32 v3, v3, v2, 32 bitop3:0x6c
	v_ashrrev_i32_e32 v2, 31, v3
	v_lshrrev_b32_e32 v2, 26, v2
	v_add_u32_e32 v5, v3, v2
	v_lshlrev_b32_e32 v6, 3, v1
	v_ashrrev_i32_e32 v2, 6, v5
	v_and_b32_e32 v6, -16, v6
	v_add_u32_e32 v6, v2, v6
	v_and_b32_e32 v7, 3, v2
	s_mov_b32 s4, 0x1fffe0
	v_lshrrev_b32_e32 v8, 2, v6
	v_lshlrev_b32_e32 v9, 1, v6
	v_and_b32_e32 v5, 0xc0, v5
	v_and_or_b32 v7, v6, s4, v7
	v_and_b32_e32 v8, 4, v8
	v_and_b32_e32 v9, 24, v9
	v_sub_u32_e32 v3, v3, v5
	v_or3_b32 v7, v7, v8, v9
	v_lshlrev_b32_e32 v8, 5, v1
	v_ashrrev_i16_sdwa v3, v213, sext(v3) dst_sel:DWORD dst_unused:UNUSED_PAD src0_sel:DWORD src1_sel:BYTE_0
	v_and_b32_e32 v8, 32, v8
	v_bfe_i32 v3, v3, 0, 16
	v_add_lshl_u32 v5, v8, v3, 1
	v_lshl_add_u32 v128, v7, 11, v5
	v_lshl_add_u32 v130, v6, 11, v5
	v_bfe_i32 v5, v0, 27, 1
	v_lshrrev_b32_e32 v5, 22, v5
	v_add_u32_e32 v5, v4, v5
	v_and_b32_e32 v5, 0xfffffc00, v5
	v_sub_u32_e32 v4, v4, v5
	v_lshrrev_b32_e32 v5, 4, v4
	v_bitop3_b32 v6, v5, v4, 32 bitop3:0x6c
	v_ashrrev_i32_e32 v5, 31, v0
	v_lshrrev_b32_e32 v5, 26, v5
	v_ashrrev_i32_e32 v4, 31, v4
	v_add_u32_e32 v5, v0, v5
	v_lshrrev_b32_e32 v4, 26, v4
	v_ashrrev_i32_e32 v5, 6, v5
	v_add_u32_e32 v4, v6, v4
	v_lshlrev_b32_e32 v7, 3, v5
	v_ashrrev_i32_e32 v4, 6, v4
	v_and_b32_e32 v7, -16, v7
	v_add_u32_e32 v7, v4, v7
	v_and_b32_e32 v8, 3, v4
	v_lshrrev_b32_e32 v9, 2, v7
	v_lshlrev_b32_e32 v10, 1, v7
	v_and_or_b32 v8, v7, s4, v8
	v_and_b32_e32 v9, 4, v9
	v_and_b32_e32 v10, 24, v10
	v_or3_b32 v8, v8, v9, v10
	v_mul_i32_i24_e32 v10, 64, v4
	v_sub_u32_e32 v6, v6, v10
	s_ashr_i32 s1, s0, 6
	v_lshlrev_b32_e32 v9, 5, v5
	v_ashrrev_i16_sdwa v6, v213, sext(v6) dst_sel:DWORD dst_unused:UNUSED_PAD src0_sel:DWORD src1_sel:BYTE_0
	s_lshl_b32 s44, s1, 10
	v_and_b32_e32 v9, 32, v9
	v_bfe_i32 v6, v6, 0, 16
	v_add_lshl_u32 v9, v9, v6, 1
	s_add_i32 s46, s44, 0
	v_readlane_b32 s4, v251, 51
	v_lshl_add_u32 v156, v8, 11, v9
	s_add_i32 m0, s46, 0x10000
	v_readlane_b32 s5, v251, 52
	v_lshl_add_u32 v132, v7, 11, v9
	s_add_i32 s47, s46, 0x2000
	s_add_i32 s48, s46, 0x4000
	s_add_i32 s49, s46, 0x6000
	s_ashr_i32 s8, s0, 8
	global_load_lds_dwordx4 v156, s[4:5]
	s_add_i32 m0, s46, 0x12000
	s_nop 0
	global_load_lds_dwordx4 v128, s[4:5]
	v_readlane_b32 s4, v251, 45
	s_add_i32 m0, s46, 0x14000
	v_readlane_b32 s5, v251, 46
	s_nop 4
	global_load_lds_dwordx4 v156, s[4:5]
	s_add_i32 m0, s46, 0x16000
	s_cmp_eq_u32 s8, 1
	global_load_lds_dwordx4 v128, s[4:5]
	v_readlane_b32 s4, v251, 47
	s_mov_b32 m0, s46
	v_readlane_b32 s5, v251, 48
	s_nop 4
	global_load_lds_dwordx4 v132, s[4:5]
	s_mov_b32 m0, s47
	s_nop 0
	global_load_lds_dwordx4 v130, s[4:5]
	v_readlane_b32 s4, v251, 49
	s_mov_b32 m0, s48
	v_readlane_b32 s5, v251, 50
	s_nop 4
	global_load_lds_dwordx4 v132, s[4:5]
	s_mov_b32 m0, s49
	s_nop 0
	global_load_lds_dwordx4 v130, s[4:5]
	s_cselect_b64 s[4:5], -1, 0
	s_cmp_lg_u32 s8, 1
	s_cbranch_scc1 .LBB0_139
	s_barrier

.LBB0_145:
	s_add_u32 s22, s18, 0xfffc0080
	s_addc_u32 s23, s19, -1
	s_add_i32 s86, 0, 0x10000
	s_cmp_eq_u32 s73, 12
	s_cselect_b32 s41, s13, s23
	s_cselect_b32 s40, s55, s22
	v_add_u32_e32 v154, s86, v143
	s_cselect_b32 s23, s11, s72
	s_cselect_b32 s22, s58, s59
	s_add_i32 vcc_lo, 0, 0x14000
	ds_read_b128 v[138:141], v154
	ds_read_b128 v[146:149], v154 offset:1024
	ds_read_b128 v[150:153], v154 offset:2048
	ds_read_b128 v[172:175], v154 offset:3072
	v_add_u32_e32 v154, vcc_lo, v143
	ds_read_b128 v[180:183], v154
	ds_read_b128 v[184:187], v154 offset:1024
	ds_read_b128 v[188:191], v154 offset:2048
	ds_read_b128 v[192:195], v154 offset:3072
	v_lshl_add_u64 v[154:155], s[18:19], 0, v[134:135]
	s_add_i32 m0, s46, 0xc000
	ds_read_b128 v[196:199], v145
	ds_read_b128 v[200:203], v145 offset:1024
	ds_read_b128 v[204:207], v145 offset:2048
	ds_read_b128 v[208:211], v145 offset:3072
	ds_read_b128 v[226:229], v145 offset:4096
	ds_read_b128 v[230:233], v145 offset:5120
	ds_read_b128 v[234:237], v145 offset:6144
	ds_read_b128 v[238:241], v145 offset:7168
	global_load_lds_dwordx4 v[154:155], off
	v_lshl_add_u64 v[154:155], s[18:19], 0, v[136:137]
	s_add_i32 m0, s46, 0xe000
	s_nop 0
	global_load_lds_dwordx4 v[154:155], off
	s_waitcnt vmcnt(8)
	s_waitcnt lgkmcnt(0)
	s_barrier
	s_waitcnt lgkmcnt(0)
	v_mfma_f32_16x16x32_bf16 v[124:127], v[138:141], v[196:199], v[124:127]
	v_mfma_f32_16x16x32_bf16 v[116:119], v[150:153], v[196:199], v[116:119]
	v_mfma_f32_16x16x32_bf16 v[108:111], v[138:141], v[204:207], v[108:111]
	v_mfma_f32_16x16x32_bf16 v[100:103], v[150:153], v[204:207], v[100:103]
	v_mfma_f32_16x16x32_bf16 v[92:95], v[138:141], v[226:229], v[92:95]
	v_mfma_f32_16x16x32_bf16 v[84:87], v[150:153], v[226:229], v[84:87]
	v_mfma_f32_16x16x32_bf16 v[76:79], v[138:141], v[234:237], v[76:79]
	v_mfma_f32_16x16x32_bf16 v[68:71], v[150:153], v[234:237], v[68:71]
	v_mfma_f32_16x16x32_bf16 v[124:127], v[146:149], v[200:203], v[124:127]
	v_mfma_f32_16x16x32_bf16 v[116:119], v[172:175], v[200:203], v[116:119]
	v_mfma_f32_16x16x32_bf16 v[108:111], v[146:149], v[208:211], v[108:111]
	v_mfma_f32_16x16x32_bf16 v[100:103], v[172:175], v[208:211], v[100:103]
	v_mfma_f32_16x16x32_bf16 v[92:95], v[146:149], v[230:233], v[92:95]
	v_mfma_f32_16x16x32_bf16 v[84:87], v[172:175], v[230:233], v[84:87]
	v_mfma_f32_16x16x32_bf16 v[76:79], v[146:149], v[238:241], v[76:79]
	v_mfma_f32_16x16x32_bf16 v[68:71], v[172:175], v[238:241], v[68:71]
	v_mfma_f32_16x16x32_bf16 v[120:123], v[180:183], v[196:199], v[120:123]
	v_mfma_f32_16x16x32_bf16 v[112:115], v[188:191], v[196:199], v[112:115]
	v_mfma_f32_16x16x32_bf16 v[104:107], v[180:183], v[204:207], v[104:107]
	v_mfma_f32_16x16x32_bf16 v[96:99], v[188:191], v[204:207], v[96:99]
	v_mfma_f32_16x16x32_bf16 v[88:91], v[180:183], v[226:229], v[88:91]
	v_mfma_f32_16x16x32_bf16 v[80:83], v[188:191], v[226:229], v[80:83]
	v_mfma_f32_16x16x32_bf16 v[72:75], v[180:183], v[234:237], v[72:75]
	v_mfma_f32_16x16x32_bf16 v[64:67], v[188:191], v[234:237], v[64:67]
	v_mfma_f32_16x16x32_bf16 v[120:123], v[184:187], v[200:203], v[120:123]
	v_mfma_f32_16x16x32_bf16 v[112:115], v[192:195], v[200:203], v[112:115]
	v_mfma_f32_16x16x32_bf16 v[104:107], v[184:187], v[208:211], v[104:107]
	v_mfma_f32_16x16x32_bf16 v[96:99], v[192:195], v[208:211], v[96:99]
	v_mfma_f32_16x16x32_bf16 v[88:91], v[184:187], v[230:233], v[88:91]
	v_mfma_f32_16x16x32_bf16 v[80:83], v[192:195], v[230:233], v[80:83]
	v_mfma_f32_16x16x32_bf16 v[72:75], v[184:187], v[238:241], v[72:75]
	v_mfma_f32_16x16x32_bf16 v[64:67], v[192:195], v[238:241], v[64:67]
	s_barrier
	s_add_i32 s86, s86, s44
	v_lshl_add_u64 v[154:155], s[22:23], 0, v[156:157]
	s_mov_b32 m0, s86
	ds_read_b128 v[196:199], v145 offset:16384
	ds_read_b128 v[200:203], v145 offset:17408
	ds_read_b128 v[204:207], v145 offset:18432
	ds_read_b128 v[208:211], v145 offset:19456
	ds_read_b128 v[226:229], v145 offset:20480
	ds_read_b128 v[230:233], v145 offset:21504
	ds_read_b128 v[234:237], v145 offset:22528
	ds_read_b128 v[238:241], v145 offset:23552
	global_load_lds_dwordx4 v[154:155], off
	s_add_i32 m0, s86, 0x2000
	s_add_u32 s86, s22, 0x40000
	v_lshl_add_u64 v[176:177], s[22:23], 0, v[128:129]
	s_addc_u32 s87, s23, 0
	s_add_i32 vcc_lo, vcc_lo, s44
	global_load_lds_dwordx4 v[176:177], off
	v_lshl_add_u64 v[242:243], s[86:87], 0, v[156:157]
	s_mov_b32 m0, vcc_lo
	v_lshl_add_u64 v[244:245], s[40:41], 0, v[130:131]
	global_load_lds_dwordx4 v[242:243], off
	v_lshl_add_u64 v[242:243], s[86:87], 0, v[128:129]
	s_add_i32 m0, vcc_lo, 0x2000
	s_nop 0
	global_load_lds_dwordx4 v[242:243], off
	v_lshl_add_u64 v[242:243], s[40:41], 0, v[132:133]
	s_mov_b32 m0, s46
	s_nop 0
	global_load_lds_dwordx4 v[242:243], off
	s_mov_b32 m0, s47
	s_nop 0
	global_load_lds_dwordx4 v[244:245], off
	s_waitcnt vmcnt(8)
	s_waitcnt lgkmcnt(0)
	s_barrier
	s_waitcnt lgkmcnt(0)
	v_mfma_f32_16x16x32_bf16 v[60:63], v[138:141], v[196:199], v[60:63]
	v_mfma_f32_16x16x32_bf16 v[52:55], v[150:153], v[196:199], v[52:55]
	v_mfma_f32_16x16x32_bf16 v[44:47], v[138:141], v[204:207], v[44:47]
	v_mfma_f32_16x16x32_bf16 v[36:39], v[150:153], v[204:207], v[36:39]
	v_mfma_f32_16x16x32_bf16 v[28:31], v[138:141], v[226:229], v[28:31]
	v_mfma_f32_16x16x32_bf16 v[20:23], v[150:153], v[226:229], v[20:23]
	v_mfma_f32_16x16x32_bf16 v[12:15], v[138:141], v[234:237], v[12:15]
	v_mfma_f32_16x16x32_bf16 v[4:7], v[150:153], v[234:237], v[4:7]
	v_mfma_f32_16x16x32_bf16 v[60:63], v[146:149], v[200:203], v[60:63]
	v_mfma_f32_16x16x32_bf16 v[52:55], v[172:175], v[200:203], v[52:55]
	v_mfma_f32_16x16x32_bf16 v[44:47], v[146:149], v[208:211], v[44:47]
	v_mfma_f32_16x16x32_bf16 v[36:39], v[172:175], v[208:211], v[36:39]
	v_mfma_f32_16x16x32_bf16 v[28:31], v[146:149], v[230:233], v[28:31]
	v_mfma_f32_16x16x32_bf16 v[20:23], v[172:175], v[230:233], v[20:23]
	v_mfma_f32_16x16x32_bf16 v[12:15], v[146:149], v[238:241], v[12:15]
	v_mfma_f32_16x16x32_bf16 v[4:7], v[172:175], v[238:241], v[4:7]
	v_mfma_f32_16x16x32_bf16 v[56:59], v[180:183], v[196:199], v[56:59]
	v_mfma_f32_16x16x32_bf16 v[48:51], v[188:191], v[196:199], v[48:51]
	v_mfma_f32_16x16x32_bf16 v[40:43], v[180:183], v[204:207], v[40:43]
	v_mfma_f32_16x16x32_bf16 v[32:35], v[188:191], v[204:207], v[32:35]
	v_mfma_f32_16x16x32_bf16 v[24:27], v[180:183], v[226:229], v[24:27]
	v_mfma_f32_16x16x32_bf16 v[16:19], v[188:191], v[226:229], v[16:19]
	v_mfma_f32_16x16x32_bf16 v[8:11], v[180:183], v[234:237], v[8:11]
	v_mfma_f32_16x16x32_bf16 v[0:3], v[188:191], v[234:237], v[0:3]
	v_mfma_f32_16x16x32_bf16 v[56:59], v[184:187], v[200:203], v[56:59]
	v_mfma_f32_16x16x32_bf16 v[48:51], v[192:195], v[200:203], v[48:51]
	v_mfma_f32_16x16x32_bf16 v[40:43], v[184:187], v[208:211], v[40:43]
	v_mfma_f32_16x16x32_bf16 v[32:35], v[192:195], v[208:211], v[32:35]
	v_mfma_f32_16x16x32_bf16 v[24:27], v[184:187], v[230:233], v[24:27]
	v_mfma_f32_16x16x32_bf16 v[16:19], v[192:195], v[230:233], v[16:19]
	v_mfma_f32_16x16x32_bf16 v[8:11], v[184:187], v[238:241], v[8:11]
	v_mfma_f32_16x16x32_bf16 v[0:3], v[192:195], v[238:241], v[0:3]
	s_barrier
	s_add_i32 s86, 0, 0x18000
	s_add_i32 s87, 0, 0x1c000
	v_add_u32_e32 v172, s86, v143
	v_add_u32_e32 v178, s87, v143
	ds_read_b128 v[138:141], v172
	ds_read_b128 v[146:149], v172 offset:1024
	ds_read_b128 v[150:153], v172 offset:2048
	ds_read_b128 v[172:175], v172 offset:3072
	ds_read_b128 v[180:183], v178
	ds_read_b128 v[184:187], v178 offset:1024
	ds_read_b128 v[188:191], v178 offset:2048
	ds_read_b128 v[192:195], v178 offset:3072
	s_add_u32 s40, s40, 0x40000
	s_addc_u32 s41, s41, 0
	s_mov_b32 m0, s48
	v_lshl_add_u64 v[246:247], s[40:41], 0, v[132:133]
	ds_read_b128 v[196:199], v145 offset:32768
	ds_read_b128 v[200:203], v145 offset:33792
	ds_read_b128 v[204:207], v145 offset:34816
	ds_read_b128 v[208:211], v145 offset:35840
	ds_read_b128 v[226:229], v145 offset:36864
	ds_read_b128 v[230:233], v145 offset:37888
	ds_read_b128 v[234:237], v145 offset:38912
	ds_read_b128 v[238:241], v145 offset:39936
	global_load_lds_dwordx4 v[246:247], off
	v_lshl_add_u64 v[246:247], s[40:41], 0, v[130:131]
	s_mov_b32 m0, s49
	s_nop 0
	global_load_lds_dwordx4 v[246:247], off
	s_waitcnt vmcnt(8)
	s_waitcnt lgkmcnt(0)
	s_barrier
	s_waitcnt lgkmcnt(0)
	v_mfma_f32_16x16x32_bf16 v[124:127], v[138:141], v[196:199], v[124:127]
	v_mfma_f32_16x16x32_bf16 v[116:119], v[150:153], v[196:199], v[116:119]
	v_mfma_f32_16x16x32_bf16 v[108:111], v[138:141], v[204:207], v[108:111]
	v_mfma_f32_16x16x32_bf16 v[100:103], v[150:153], v[204:207], v[100:103]
	v_mfma_f32_16x16x32_bf16 v[92:95], v[138:141], v[226:229], v[92:95]
	v_mfma_f32_16x16x32_bf16 v[84:87], v[150:153], v[226:229], v[84:87]
	v_mfma_f32_16x16x32_bf16 v[76:79], v[138:141], v[234:237], v[76:79]
	v_mfma_f32_16x16x32_bf16 v[68:71], v[150:153], v[234:237], v[68:71]
	v_mfma_f32_16x16x32_bf16 v[124:127], v[146:149], v[200:203], v[124:127]
	v_mfma_f32_16x16x32_bf16 v[116:119], v[172:175], v[200:203], v[116:119]
	v_mfma_f32_16x16x32_bf16 v[108:111], v[146:149], v[208:211], v[108:111]
	v_mfma_f32_16x16x32_bf16 v[100:103], v[172:175], v[208:211], v[100:103]
	v_mfma_f32_16x16x32_bf16 v[92:95], v[146:149], v[230:233], v[92:95]
	v_mfma_f32_16x16x32_bf16 v[84:87], v[172:175], v[230:233], v[84:87]
	v_mfma_f32_16x16x32_bf16 v[76:79], v[146:149], v[238:241], v[76:79]
	v_mfma_f32_16x16x32_bf16 v[68:71], v[172:175], v[238:241], v[68:71]
	v_mfma_f32_16x16x32_bf16 v[120:123], v[180:183], v[196:199], v[120:123]
	v_mfma_f32_16x16x32_bf16 v[112:115], v[188:191], v[196:199], v[112:115]
	v_mfma_f32_16x16x32_bf16 v[104:107], v[180:183], v[204:207], v[104:107]
	v_mfma_f32_16x16x32_bf16 v[96:99], v[188:191], v[204:207], v[96:99]
	v_mfma_f32_16x16x32_bf16 v[88:91], v[180:183], v[226:229], v[88:91]
	v_mfma_f32_16x16x32_bf16 v[80:83], v[188:191], v[226:229], v[80:83]
	v_mfma_f32_16x16x32_bf16 v[72:75], v[180:183], v[234:237], v[72:75]
	v_mfma_f32_16x16x32_bf16 v[64:67], v[188:191], v[234:237], v[64:67]
	v_mfma_f32_16x16x32_bf16 v[120:123], v[184:187], v[200:203], v[120:123]
	v_mfma_f32_16x16x32_bf16 v[112:115], v[192:195], v[200:203], v[112:115]
	v_mfma_f32_16x16x32_bf16 v[104:107], v[184:187], v[208:211], v[104:107]
	v_mfma_f32_16x16x32_bf16 v[96:99], v[192:195], v[208:211], v[96:99]
	v_mfma_f32_16x16x32_bf16 v[88:91], v[184:187], v[230:233], v[88:91]
	v_mfma_f32_16x16x32_bf16 v[80:83], v[192:195], v[230:233], v[80:83]
	v_mfma_f32_16x16x32_bf16 v[72:75], v[184:187], v[238:241], v[72:75]
	v_mfma_f32_16x16x32_bf16 v[64:67], v[192:195], v[238:241], v[64:67]
	s_barrier
	s_add_i32 s40, s86, s44
	v_lshl_add_u64 v[154:155], v[154:155], 0, s[64:65]
	s_mov_b32 m0, s40
	ds_read_b128 v[196:199], v145 offset:49152
	ds_read_b128 v[200:203], v145 offset:50176
	ds_read_b128 v[204:207], v145 offset:51200
	ds_read_b128 v[208:211], v145 offset:52224
	ds_read_b128 v[226:229], v145 offset:53248
	ds_read_b128 v[230:233], v145 offset:54272
	ds_read_b128 v[234:237], v145 offset:55296
	ds_read_b128 v[238:241], v145 offset:56320
	global_load_lds_dwordx4 v[154:155], off
	s_add_i32 m0, s40, 0x2000
	s_add_u32 s22, s22, 0x40080
	v_lshl_add_u64 v[154:155], v[176:177], 0, s[64:65]
	s_addc_u32 s23, s23, 0
	s_add_i32 s40, s87, s44
	global_load_lds_dwordx4 v[154:155], off
	v_lshl_add_u64 v[154:155], s[22:23], 0, v[156:157]
	s_mov_b32 m0, s40
	s_nop 0
	global_load_lds_dwordx4 v[154:155], off
	v_lshl_add_u64 v[154:155], s[22:23], 0, v[128:129]
	s_add_i32 m0, s40, 0x2000
	s_nop 0
	global_load_lds_dwordx4 v[154:155], off
	v_lshl_add_u64 v[154:155], v[242:243], 0, s[64:65]
	s_mov_b32 m0, s50
	s_nop 0
	global_load_lds_dwordx4 v[154:155], off
	v_lshl_add_u64 v[154:155], v[244:245], 0, s[64:65]
	s_mov_b32 m0, s51
	s_nop 0
	global_load_lds_dwordx4 v[154:155], off
	s_waitcnt vmcnt(8)
	s_waitcnt lgkmcnt(0)
	s_barrier
	s_waitcnt lgkmcnt(0)
	v_mfma_f32_16x16x32_bf16 v[60:63], v[138:141], v[196:199], v[60:63]
	v_mfma_f32_16x16x32_bf16 v[52:55], v[150:153], v[196:199], v[52:55]
	v_mfma_f32_16x16x32_bf16 v[44:47], v[138:141], v[204:207], v[44:47]
	v_mfma_f32_16x16x32_bf16 v[36:39], v[150:153], v[204:207], v[36:39]
	v_mfma_f32_16x16x32_bf16 v[28:31], v[138:141], v[226:229], v[28:31]
	v_mfma_f32_16x16x32_bf16 v[20:23], v[150:153], v[226:229], v[20:23]
	v_mfma_f32_16x16x32_bf16 v[12:15], v[138:141], v[234:237], v[12:15]
	v_mfma_f32_16x16x32_bf16 v[4:7], v[150:153], v[234:237], v[4:7]
	v_mfma_f32_16x16x32_bf16 v[60:63], v[146:149], v[200:203], v[60:63]
	v_mfma_f32_16x16x32_bf16 v[52:55], v[172:175], v[200:203], v[52:55]
	v_mfma_f32_16x16x32_bf16 v[44:47], v[146:149], v[208:211], v[44:47]
	v_mfma_f32_16x16x32_bf16 v[36:39], v[172:175], v[208:211], v[36:39]
	v_mfma_f32_16x16x32_bf16 v[28:31], v[146:149], v[230:233], v[28:31]
	v_mfma_f32_16x16x32_bf16 v[20:23], v[172:175], v[230:233], v[20:23]
	v_mfma_f32_16x16x32_bf16 v[12:15], v[146:149], v[238:241], v[12:15]
	v_mfma_f32_16x16x32_bf16 v[4:7], v[172:175], v[238:241], v[4:7]
	v_mfma_f32_16x16x32_bf16 v[56:59], v[180:183], v[196:199], v[56:59]
	v_mfma_f32_16x16x32_bf16 v[48:51], v[188:191], v[196:199], v[48:51]
	v_mfma_f32_16x16x32_bf16 v[40:43], v[180:183], v[204:207], v[40:43]
	v_mfma_f32_16x16x32_bf16 v[32:35], v[188:191], v[204:207], v[32:35]
	v_mfma_f32_16x16x32_bf16 v[24:27], v[180:183], v[226:229], v[24:27]
	v_mfma_f32_16x16x32_bf16 v[16:19], v[188:191], v[226:229], v[16:19]
	v_mfma_f32_16x16x32_bf16 v[8:11], v[180:183], v[234:237], v[8:11]
	v_mfma_f32_16x16x32_bf16 v[0:3], v[188:191], v[234:237], v[0:3]
	v_mfma_f32_16x16x32_bf16 v[56:59], v[184:187], v[200:203], v[56:59]
	v_mfma_f32_16x16x32_bf16 v[48:51], v[192:195], v[200:203], v[48:51]
	v_mfma_f32_16x16x32_bf16 v[40:43], v[184:187], v[208:211], v[40:43]
	v_mfma_f32_16x16x32_bf16 v[32:35], v[192:195], v[208:211], v[32:35]
	v_mfma_f32_16x16x32_bf16 v[24:27], v[184:187], v[230:233], v[24:27]
	v_mfma_f32_16x16x32_bf16 v[16:19], v[192:195], v[230:233], v[16:19]
	v_mfma_f32_16x16x32_bf16 v[8:11], v[184:187], v[238:241], v[8:11]
	v_mfma_f32_16x16x32_bf16 v[0:3], v[192:195], v[238:241], v[0:3]
	s_barrier
	s_add_i32 s73, s73, 2
	s_add_u32 s18, s18, 0x100
	s_addc_u32 s19, s19, 0
	s_add_u32 s59, s59, 0x100
	s_addc_u32 s72, s72, 0
	s_cmp_gt_u32 s73, 13
	s_cbranch_scc0 .LBB0_145
	s_and_b64 vcc, exec, s[8:9]
	s_cbranch_vccz .LBB0_148
	s_barrier

.LBB0_151:
	s_waitcnt vmcnt(0)
	s_setprio 0
	v_readlane_b32 s22, v249, 25
	v_readlane_b32 s50, v253, 21
	v_readlane_b32 s48, v253, 23
	v_readlane_b32 s52, v253, 25
	v_readlane_b32 s23, v249, 26
	v_readlane_b32 s51, v253, 22
	v_readlane_b32 s49, v253, 24
	v_readlane_b32 s53, v253, 26
	s_barrier

.LBB0_204:
	s_or_b64 exec, exec, s[0:1]
	v_readlane_b32 s0, v250, 53
	v_readlane_b32 s1, v250, 54
	v_mov_b32_e32 v8, v179
	s_waitcnt lgkmcnt(0)
	v_cndmask_b32_e64 v0, 0, 1, s[0:1]
	s_barrier
	v_cmp_ne_u32_e64 s[74:75], 1, v0
	s_andn2_b64 vcc, exec, s[0:1]
	v_readfirstlane_b32 s0, v8
	s_cbranch_vccnz .LBB0_228
	v_readfirstlane_b32 s100, v179
	s_lshr_b32 s100, s100, 6
	s_cmp_ge_u32 s100, 4
	s_cbranch_scc0 .Lprio_done1
	s_setprio 1
.Lprio_done1:
	v_lshlrev_b32_e32 v4, 4, v8
	v_add_u32_e32 v1, 0x2000, v4
	v_ashrrev_i32_e32 v0, 31, v1
	v_lshrrev_b32_e32 v0, 22, v0
	v_add_u32_e32 v0, v1, v0
	v_ashrrev_i32_e32 v0, 10, v0
	v_mul_i32_i24_e32 v2, 0x400, v0
	v_sub_u32_e32 v1, v1, v2
	v_lshrrev_b32_e32 v2, 4, v1
	v_bitop3_b32 v3, v2, v1, 32 bitop3:0x6c
	v_ashrrev_i32_e32 v1, 31, v3
	v_lshrrev_b32_e32 v1, 26, v1
	v_add_u32_e32 v5, v3, v1
	v_ashrrev_i32_e32 v1, 6, v5
	v_and_b32_e32 v5, 0xc0, v5
	v_sub_u32_e32 v3, v3, v5
	v_bfe_i32 v5, v8, 27, 1
	v_lshrrev_b32_e32 v5, 22, v5
	v_add_u32_e32 v5, v4, v5
	v_and_b32_e32 v5, 0xfffffc00, v5
	v_lshlrev_b32_e32 v2, 3, v0
	v_sub_u32_e32 v4, v4, v5
	v_and_b32_e32 v2, 0xfffff0, v2
	v_lshrrev_b32_e32 v5, 4, v4
	v_add_u32_e32 v2, v1, v2
	s_movk_i32 s4, 0xb00
	v_bitop3_b32 v7, v5, v4, 32 bitop3:0x6c
	v_ashrrev_i32_e32 v5, 31, v8
	v_mul_lo_u32 v6, v2, s4
	v_lshlrev_b32_e32 v2, 5, v0
	v_lshrrev_b32_e32 v5, 26, v5
	v_and_b32_e32 v2, 32, v2
	v_ashrrev_i16_sdwa v3, v213, sext(v3) dst_sel:DWORD dst_unused:UNUSED_PAD src0_sel:DWORD src1_sel:BYTE_0
	v_ashrrev_i32_e32 v4, 31, v4
	v_add_u32_e32 v5, v8, v5
	v_or_b32_e32 v6, v6, v2
	v_bfe_i32 v3, v3, 0, 16
	v_lshrrev_b32_e32 v4, 26, v4
	v_ashrrev_i32_e32 v5, 6, v5
	v_add_lshl_u32 v128, v6, v3, 1
	v_add_u32_e32 v4, v7, v4
	v_lshlrev_b32_e32 v6, 3, v5
	v_ashrrev_i32_e32 v4, 6, v4
	v_and_b32_e32 v6, 0xfffff0, v6
	v_add_u32_e32 v6, v4, v6
	v_mul_i32_i24_e32 v10, 64, v4
	s_ashr_i32 s1, s0, 6
	v_mul_lo_u32 v9, v6, s4
	v_lshlrev_b32_e32 v6, 5, v5
	v_sub_u32_e32 v7, v7, v10
	s_lshl_b32 s40, s1, 10
	v_and_b32_e32 v6, 32, v6
	v_ashrrev_i16_sdwa v7, v213, sext(v7) dst_sel:DWORD dst_unused:UNUSED_PAD src0_sel:DWORD src1_sel:BYTE_0
	v_or_b32_e32 v9, v9, v6
	v_bfe_i32 v7, v7, 0, 16
	s_add_i32 s41, s40, 0
	v_readlane_b32 s4, v252, 0
	v_add_lshl_u32 v156, v9, v7, 1
	s_add_i32 m0, s41, 0x10000
	v_readlane_b32 s5, v252, 1
	s_add_i32 s44, s41, 0x2000
	s_add_i32 s46, s41, 0x4000
	s_add_i32 s47, s41, 0x6000
	s_mov_b32 s12, 0xb000
	s_nop 0
	global_load_lds_dwordx4 v156, s[4:5]
	s_add_i32 m0, s41, 0x12000
	s_nop 0
	global_load_lds_dwordx4 v128, s[4:5]
	v_readlane_b32 s4, v251, 58
	s_add_i32 m0, s41, 0x14000
	v_readlane_b32 s5, v251, 59
	s_nop 4
	global_load_lds_dwordx4 v156, s[4:5]
	s_add_i32 m0, s41, 0x16000
	s_nop 0
	global_load_lds_dwordx4 v128, s[4:5]
	v_readlane_b32 s4, v251, 60
	s_mov_b32 m0, s41
	v_readlane_b32 s5, v251, 61
	s_nop 4
	global_load_lds_dwordx4 v156, s[4:5]
	s_mov_b32 m0, s44
	s_nop 0
	global_load_lds_dwordx4 v128, s[4:5]
	v_readlane_b32 s4, v251, 62
	s_mov_b32 m0, s46
	v_readlane_b32 s5, v251, 63
	s_nop 4
	global_load_lds_dwordx4 v156, s[4:5]
	s_mov_b32 m0, s47
	s_nop 0
	global_load_lds_dwordx4 v128, s[4:5]
	s_ashr_i32 s4, s0, 8
	s_cmp_eq_u32 s4, 1
	s_cselect_b64 s[8:9], -1, 0
	s_cmp_lg_u32 s4, 1
	s_cbranch_scc1 .LBB0_207
	s_barrier

.LBB0_221:
	s_add_u32 s16, s14, 0x100
	s_addc_u32 s17, s15, 0
	s_add_i32 s86, 0, 0x10000
	s_cmp_eq_u32 s73, 40
	s_cselect_b32 s23, s5, s17
	s_cselect_b32 s22, s4, s16
	s_cselect_b32 s19, s13, s72
	s_cselect_b32 s18, s12, s59
	s_add_i32 s87, 0, 0x14000
	v_add_u32_e32 v150, s86, v143
	v_add_u32_e32 v154, s87, v143
	ds_read_b128 v[134:137], v150
	ds_read_b128 v[138:141], v150 offset:1024
	ds_read_b128 v[146:149], v150 offset:2048
	ds_read_b128 v[150:153], v150 offset:3072
	ds_read_b128 v[172:175], v154
	ds_read_b128 v[180:183], v154 offset:1024
	ds_read_b128 v[184:187], v154 offset:2048
	ds_read_b128 v[188:191], v154 offset:3072
	v_lshl_add_u64 v[154:155], s[14:15], 0, v[130:131]
	s_add_i32 m0, s41, 0xc000
	ds_read_b128 v[192:195], v145
	ds_read_b128 v[196:199], v145 offset:1024
	ds_read_b128 v[200:203], v145 offset:2048
	ds_read_b128 v[204:207], v145 offset:3072
	ds_read_b128 v[208:211], v145 offset:4096
	ds_read_b128 v[226:229], v145 offset:5120
	ds_read_b128 v[230:233], v145 offset:6144
	ds_read_b128 v[234:237], v145 offset:7168
	global_load_lds_dwordx4 v[154:155], off
	v_lshl_add_u64 v[154:155], s[14:15], 0, v[132:133]
	s_add_i32 m0, s41, 0xe000
	s_nop 0
	global_load_lds_dwordx4 v[154:155], off
	s_waitcnt vmcnt(8)
	s_waitcnt lgkmcnt(0)
	s_barrier
	s_waitcnt lgkmcnt(0)
	v_mfma_f32_16x16x32_bf16 v[124:127], v[134:137], v[192:195], v[124:127]
	v_mfma_f32_16x16x32_bf16 v[120:123], v[146:149], v[192:195], v[120:123]
	v_mfma_f32_16x16x32_bf16 v[112:115], v[134:137], v[200:203], v[112:115]
	v_mfma_f32_16x16x32_bf16 v[108:111], v[146:149], v[200:203], v[108:111]
	v_mfma_f32_16x16x32_bf16 v[96:99], v[134:137], v[208:211], v[96:99]
	v_mfma_f32_16x16x32_bf16 v[92:95], v[146:149], v[208:211], v[92:95]
	v_mfma_f32_16x16x32_bf16 v[80:83], v[134:137], v[230:233], v[80:83]
	v_mfma_f32_16x16x32_bf16 v[76:79], v[146:149], v[230:233], v[76:79]
	v_mfma_f32_16x16x32_bf16 v[124:127], v[138:141], v[196:199], v[124:127]
	v_mfma_f32_16x16x32_bf16 v[120:123], v[150:153], v[196:199], v[120:123]
	v_mfma_f32_16x16x32_bf16 v[112:115], v[138:141], v[204:207], v[112:115]
	v_mfma_f32_16x16x32_bf16 v[108:111], v[150:153], v[204:207], v[108:111]
	v_mfma_f32_16x16x32_bf16 v[96:99], v[138:141], v[226:229], v[96:99]
	v_mfma_f32_16x16x32_bf16 v[92:95], v[150:153], v[226:229], v[92:95]
	v_mfma_f32_16x16x32_bf16 v[80:83], v[138:141], v[234:237], v[80:83]
	v_mfma_f32_16x16x32_bf16 v[76:79], v[150:153], v[234:237], v[76:79]
	v_mfma_f32_16x16x32_bf16 v[116:119], v[172:175], v[192:195], v[116:119]
	v_mfma_f32_16x16x32_bf16 v[104:107], v[184:187], v[192:195], v[104:107]
	v_mfma_f32_16x16x32_bf16 v[100:103], v[172:175], v[200:203], v[100:103]
	v_mfma_f32_16x16x32_bf16 v[88:91], v[184:187], v[200:203], v[88:91]
	v_mfma_f32_16x16x32_bf16 v[84:87], v[172:175], v[208:211], v[84:87]
	v_mfma_f32_16x16x32_bf16 v[72:75], v[184:187], v[208:211], v[72:75]
	v_mfma_f32_16x16x32_bf16 v[68:71], v[172:175], v[230:233], v[68:71]
	v_mfma_f32_16x16x32_bf16 v[64:67], v[184:187], v[230:233], v[64:67]
	v_mfma_f32_16x16x32_bf16 v[116:119], v[180:183], v[196:199], v[116:119]
	v_mfma_f32_16x16x32_bf16 v[104:107], v[188:191], v[196:199], v[104:107]
	v_mfma_f32_16x16x32_bf16 v[100:103], v[180:183], v[204:207], v[100:103]
	v_mfma_f32_16x16x32_bf16 v[88:91], v[188:191], v[204:207], v[88:91]
	v_mfma_f32_16x16x32_bf16 v[84:87], v[180:183], v[226:229], v[84:87]
	v_mfma_f32_16x16x32_bf16 v[72:75], v[188:191], v[226:229], v[72:75]
	v_mfma_f32_16x16x32_bf16 v[68:71], v[180:183], v[234:237], v[68:71]
	v_mfma_f32_16x16x32_bf16 v[64:67], v[188:191], v[234:237], v[64:67]
	s_barrier
	s_add_i32 s14, s86, s40
	v_lshl_add_u64 v[154:155], s[18:19], 0, v[156:157]
	s_mov_b32 m0, s14
	ds_read_b128 v[192:195], v145 offset:16384
	ds_read_b128 v[196:199], v145 offset:17408
	ds_read_b128 v[200:203], v145 offset:18432
	ds_read_b128 v[204:207], v145 offset:19456
	ds_read_b128 v[208:211], v145 offset:20480
	ds_read_b128 v[226:229], v145 offset:21504
	ds_read_b128 v[230:233], v145 offset:22528
	ds_read_b128 v[234:237], v145 offset:23552
	global_load_lds_dwordx4 v[154:155], off
	s_add_i32 m0, s14, 0x2000
	s_add_u32 s14, s18, 0xb0000
	v_lshl_add_u64 v[176:177], s[18:19], 0, v[128:129]
	s_addc_u32 s15, s19, 0
	s_add_i32 s86, s87, s40
	global_load_lds_dwordx4 v[176:177], off
	v_lshl_add_u64 v[238:239], s[14:15], 0, v[156:157]
	s_mov_b32 m0, s86
	v_lshl_add_u64 v[240:241], s[22:23], 0, v[128:129]
	global_load_lds_dwordx4 v[238:239], off
	v_lshl_add_u64 v[238:239], s[14:15], 0, v[128:129]
	s_add_i32 m0, s86, 0x2000
	s_nop 0
	global_load_lds_dwordx4 v[238:239], off
	v_lshl_add_u64 v[238:239], s[22:23], 0, v[156:157]
	s_mov_b32 m0, s41
	s_nop 0
	global_load_lds_dwordx4 v[238:239], off
	s_mov_b32 m0, s44
	s_nop 0
	global_load_lds_dwordx4 v[240:241], off
	s_waitcnt vmcnt(8)
	s_waitcnt lgkmcnt(0)
	s_barrier
	s_waitcnt lgkmcnt(0)
	v_mfma_f32_16x16x32_bf16 v[60:63], v[134:137], v[192:195], v[60:63]
	v_mfma_f32_16x16x32_bf16 v[56:59], v[146:149], v[192:195], v[56:59]
	v_mfma_f32_16x16x32_bf16 v[48:51], v[134:137], v[200:203], v[48:51]
	v_mfma_f32_16x16x32_bf16 v[44:47], v[146:149], v[200:203], v[44:47]
	v_mfma_f32_16x16x32_bf16 v[32:35], v[134:137], v[208:211], v[32:35]
	v_mfma_f32_16x16x32_bf16 v[28:31], v[146:149], v[208:211], v[28:31]
	v_mfma_f32_16x16x32_bf16 v[16:19], v[134:137], v[230:233], v[16:19]
	v_mfma_f32_16x16x32_bf16 v[12:15], v[146:149], v[230:233], v[12:15]
	v_mfma_f32_16x16x32_bf16 v[60:63], v[138:141], v[196:199], v[60:63]
	v_mfma_f32_16x16x32_bf16 v[56:59], v[150:153], v[196:199], v[56:59]
	v_mfma_f32_16x16x32_bf16 v[48:51], v[138:141], v[204:207], v[48:51]
	v_mfma_f32_16x16x32_bf16 v[44:47], v[150:153], v[204:207], v[44:47]
	v_mfma_f32_16x16x32_bf16 v[32:35], v[138:141], v[226:229], v[32:35]
	v_mfma_f32_16x16x32_bf16 v[28:31], v[150:153], v[226:229], v[28:31]
	v_mfma_f32_16x16x32_bf16 v[16:19], v[138:141], v[234:237], v[16:19]
	v_mfma_f32_16x16x32_bf16 v[12:15], v[150:153], v[234:237], v[12:15]
	v_mfma_f32_16x16x32_bf16 v[52:55], v[172:175], v[192:195], v[52:55]
	v_mfma_f32_16x16x32_bf16 v[40:43], v[184:187], v[192:195], v[40:43]
	v_mfma_f32_16x16x32_bf16 v[36:39], v[172:175], v[200:203], v[36:39]
	v_mfma_f32_16x16x32_bf16 v[24:27], v[184:187], v[200:203], v[24:27]
	v_mfma_f32_16x16x32_bf16 v[20:23], v[172:175], v[208:211], v[20:23]
	v_mfma_f32_16x16x32_bf16 v[8:11], v[184:187], v[208:211], v[8:11]
	v_mfma_f32_16x16x32_bf16 v[4:7], v[172:175], v[230:233], v[4:7]
	v_mfma_f32_16x16x32_bf16 v[0:3], v[184:187], v[230:233], v[0:3]
	v_mfma_f32_16x16x32_bf16 v[52:55], v[180:183], v[196:199], v[52:55]
	v_mfma_f32_16x16x32_bf16 v[40:43], v[188:191], v[196:199], v[40:43]
	v_mfma_f32_16x16x32_bf16 v[36:39], v[180:183], v[204:207], v[36:39]
	v_mfma_f32_16x16x32_bf16 v[24:27], v[188:191], v[204:207], v[24:27]
	v_mfma_f32_16x16x32_bf16 v[20:23], v[180:183], v[226:229], v[20:23]
	v_mfma_f32_16x16x32_bf16 v[8:11], v[188:191], v[226:229], v[8:11]
	v_mfma_f32_16x16x32_bf16 v[4:7], v[180:183], v[234:237], v[4:7]
	v_mfma_f32_16x16x32_bf16 v[0:3], v[188:191], v[234:237], v[0:3]
	s_barrier
	s_add_i32 s86, 0, 0x18000
	s_add_i32 s87, 0, 0x1c000
	v_add_u32_e32 v150, s86, v143
	v_add_u32_e32 v178, s87, v143
	ds_read_b128 v[134:137], v150
	ds_read_b128 v[138:141], v150 offset:1024
	ds_read_b128 v[146:149], v150 offset:2048
	ds_read_b128 v[150:153], v150 offset:3072
	ds_read_b128 v[172:175], v178
	ds_read_b128 v[180:183], v178 offset:1024
	ds_read_b128 v[184:187], v178 offset:2048
	ds_read_b128 v[188:191], v178 offset:3072
	s_add_u32 s14, s22, 0xb0000
	s_addc_u32 s15, s23, 0
	s_mov_b32 m0, s46
	v_lshl_add_u64 v[242:243], s[14:15], 0, v[156:157]
	ds_read_b128 v[192:195], v145 offset:32768
	ds_read_b128 v[196:199], v145 offset:33792
	ds_read_b128 v[200:203], v145 offset:34816
	ds_read_b128 v[204:207], v145 offset:35840
	ds_read_b128 v[208:211], v145 offset:36864
	ds_read_b128 v[226:229], v145 offset:37888
	ds_read_b128 v[230:233], v145 offset:38912
	ds_read_b128 v[234:237], v145 offset:39936
	global_load_lds_dwordx4 v[242:243], off
	v_lshl_add_u64 v[242:243], s[14:15], 0, v[128:129]
	s_mov_b32 m0, s47
	s_nop 0
	global_load_lds_dwordx4 v[242:243], off
	s_waitcnt vmcnt(8)
	s_waitcnt lgkmcnt(0)
	s_barrier
	s_waitcnt lgkmcnt(0)
	v_mfma_f32_16x16x32_bf16 v[124:127], v[134:137], v[192:195], v[124:127]
	v_mfma_f32_16x16x32_bf16 v[120:123], v[146:149], v[192:195], v[120:123]
	v_mfma_f32_16x16x32_bf16 v[112:115], v[134:137], v[200:203], v[112:115]
	v_mfma_f32_16x16x32_bf16 v[108:111], v[146:149], v[200:203], v[108:111]
	v_mfma_f32_16x16x32_bf16 v[96:99], v[134:137], v[208:211], v[96:99]
	v_mfma_f32_16x16x32_bf16 v[92:95], v[146:149], v[208:211], v[92:95]
	v_mfma_f32_16x16x32_bf16 v[80:83], v[134:137], v[230:233], v[80:83]
	v_mfma_f32_16x16x32_bf16 v[76:79], v[146:149], v[230:233], v[76:79]
	v_mfma_f32_16x16x32_bf16 v[124:127], v[138:141], v[196:199], v[124:127]
	v_mfma_f32_16x16x32_bf16 v[120:123], v[150:153], v[196:199], v[120:123]
	v_mfma_f32_16x16x32_bf16 v[112:115], v[138:141], v[204:207], v[112:115]
	v_mfma_f32_16x16x32_bf16 v[108:111], v[150:153], v[204:207], v[108:111]
	v_mfma_f32_16x16x32_bf16 v[96:99], v[138:141], v[226:229], v[96:99]
	v_mfma_f32_16x16x32_bf16 v[92:95], v[150:153], v[226:229], v[92:95]
	v_mfma_f32_16x16x32_bf16 v[80:83], v[138:141], v[234:237], v[80:83]
	v_mfma_f32_16x16x32_bf16 v[76:79], v[150:153], v[234:237], v[76:79]
	v_mfma_f32_16x16x32_bf16 v[116:119], v[172:175], v[192:195], v[116:119]
	v_mfma_f32_16x16x32_bf16 v[104:107], v[184:187], v[192:195], v[104:107]
	v_mfma_f32_16x16x32_bf16 v[100:103], v[172:175], v[200:203], v[100:103]
	v_mfma_f32_16x16x32_bf16 v[88:91], v[184:187], v[200:203], v[88:91]
	v_mfma_f32_16x16x32_bf16 v[84:87], v[172:175], v[208:211], v[84:87]
	v_mfma_f32_16x16x32_bf16 v[72:75], v[184:187], v[208:211], v[72:75]
	v_mfma_f32_16x16x32_bf16 v[68:71], v[172:175], v[230:233], v[68:71]
	v_mfma_f32_16x16x32_bf16 v[64:67], v[184:187], v[230:233], v[64:67]
	v_mfma_f32_16x16x32_bf16 v[116:119], v[180:183], v[196:199], v[116:119]
	v_mfma_f32_16x16x32_bf16 v[104:107], v[188:191], v[196:199], v[104:107]
	v_mfma_f32_16x16x32_bf16 v[100:103], v[180:183], v[204:207], v[100:103]
	v_mfma_f32_16x16x32_bf16 v[88:91], v[188:191], v[204:207], v[88:91]
	v_mfma_f32_16x16x32_bf16 v[84:87], v[180:183], v[226:229], v[84:87]
	v_mfma_f32_16x16x32_bf16 v[72:75], v[188:191], v[226:229], v[72:75]
	v_mfma_f32_16x16x32_bf16 v[68:71], v[180:183], v[234:237], v[68:71]
	v_mfma_f32_16x16x32_bf16 v[64:67], v[188:191], v[234:237], v[64:67]
	s_barrier
	s_add_i32 s14, s86, s40
	v_lshl_add_u64 v[154:155], v[154:155], 0, s[64:65]
	s_mov_b32 m0, s14
	ds_read_b128 v[192:195], v145 offset:49152
	ds_read_b128 v[196:199], v145 offset:50176
	ds_read_b128 v[200:203], v145 offset:51200
	ds_read_b128 v[204:207], v145 offset:52224
	ds_read_b128 v[208:211], v145 offset:53248
	ds_read_b128 v[226:229], v145 offset:54272
	ds_read_b128 v[230:233], v145 offset:55296
	ds_read_b128 v[234:237], v145 offset:56320
	global_load_lds_dwordx4 v[154:155], off
	s_add_i32 m0, s14, 0x2000
	s_add_u32 s14, s18, 0xb0080
	v_lshl_add_u64 v[154:155], v[176:177], 0, s[64:65]
	s_addc_u32 s15, s19, 0
	s_add_i32 s18, s87, s40
	global_load_lds_dwordx4 v[154:155], off
	v_lshl_add_u64 v[154:155], s[14:15], 0, v[156:157]
	s_mov_b32 m0, s18
	s_nop 0
	global_load_lds_dwordx4 v[154:155], off
	v_lshl_add_u64 v[154:155], s[14:15], 0, v[128:129]
	s_add_i32 m0, s18, 0x2000
	s_nop 0
	global_load_lds_dwordx4 v[154:155], off
	v_lshl_add_u64 v[154:155], v[238:239], 0, s[64:65]
	s_mov_b32 m0, s50
	s_nop 0
	global_load_lds_dwordx4 v[154:155], off
	v_lshl_add_u64 v[154:155], v[240:241], 0, s[64:65]
	s_mov_b32 m0, s51
	s_nop 0
	global_load_lds_dwordx4 v[154:155], off
	s_waitcnt vmcnt(8)
	s_waitcnt lgkmcnt(0)
	s_barrier
	s_waitcnt lgkmcnt(0)
	v_mfma_f32_16x16x32_bf16 v[60:63], v[134:137], v[192:195], v[60:63]
	v_mfma_f32_16x16x32_bf16 v[56:59], v[146:149], v[192:195], v[56:59]
	v_mfma_f32_16x16x32_bf16 v[48:51], v[134:137], v[200:203], v[48:51]
	v_mfma_f32_16x16x32_bf16 v[44:47], v[146:149], v[200:203], v[44:47]
	v_mfma_f32_16x16x32_bf16 v[32:35], v[134:137], v[208:211], v[32:35]
	v_mfma_f32_16x16x32_bf16 v[28:31], v[146:149], v[208:211], v[28:31]
	v_mfma_f32_16x16x32_bf16 v[16:19], v[134:137], v[230:233], v[16:19]
	v_mfma_f32_16x16x32_bf16 v[12:15], v[146:149], v[230:233], v[12:15]
	v_mfma_f32_16x16x32_bf16 v[60:63], v[138:141], v[196:199], v[60:63]
	v_mfma_f32_16x16x32_bf16 v[56:59], v[150:153], v[196:199], v[56:59]
	v_mfma_f32_16x16x32_bf16 v[48:51], v[138:141], v[204:207], v[48:51]
	v_mfma_f32_16x16x32_bf16 v[44:47], v[150:153], v[204:207], v[44:47]
	v_mfma_f32_16x16x32_bf16 v[32:35], v[138:141], v[226:229], v[32:35]
	v_mfma_f32_16x16x32_bf16 v[28:31], v[150:153], v[226:229], v[28:31]
	v_mfma_f32_16x16x32_bf16 v[16:19], v[138:141], v[234:237], v[16:19]
	v_mfma_f32_16x16x32_bf16 v[12:15], v[150:153], v[234:237], v[12:15]
	v_mfma_f32_16x16x32_bf16 v[52:55], v[172:175], v[192:195], v[52:55]
	v_mfma_f32_16x16x32_bf16 v[40:43], v[184:187], v[192:195], v[40:43]
	v_mfma_f32_16x16x32_bf16 v[36:39], v[172:175], v[200:203], v[36:39]
	v_mfma_f32_16x16x32_bf16 v[24:27], v[184:187], v[200:203], v[24:27]
	v_mfma_f32_16x16x32_bf16 v[20:23], v[172:175], v[208:211], v[20:23]
	v_mfma_f32_16x16x32_bf16 v[8:11], v[184:187], v[208:211], v[8:11]
	v_mfma_f32_16x16x32_bf16 v[4:7], v[172:175], v[230:233], v[4:7]
	v_mfma_f32_16x16x32_bf16 v[0:3], v[184:187], v[230:233], v[0:3]
	v_mfma_f32_16x16x32_bf16 v[52:55], v[180:183], v[196:199], v[52:55]
	v_mfma_f32_16x16x32_bf16 v[40:43], v[188:191], v[196:199], v[40:43]
	v_mfma_f32_16x16x32_bf16 v[36:39], v[180:183], v[204:207], v[36:39]
	v_mfma_f32_16x16x32_bf16 v[24:27], v[188:191], v[204:207], v[24:27]
	v_mfma_f32_16x16x32_bf16 v[20:23], v[180:183], v[226:229], v[20:23]
	v_mfma_f32_16x16x32_bf16 v[8:11], v[188:191], v[226:229], v[8:11]
	v_mfma_f32_16x16x32_bf16 v[4:7], v[180:183], v[234:237], v[4:7]
	v_mfma_f32_16x16x32_bf16 v[0:3], v[188:191], v[234:237], v[0:3]
	s_barrier
	s_add_i32 s73, s73, 2
	s_add_u32 s59, s59, 0x100
	s_addc_u32 s72, s72, 0
	s_cmp_gt_u32 s73, 41
	s_mov_b64 s[14:15], s[16:17]
	s_cbranch_scc0 .LBB0_221
	s_and_b64 vcc, exec, s[10:11]
	s_cbranch_vccz .LBB0_224
	s_barrier

.LBB0_352:
	s_or_b64 exec, exec, s[0:1]
	v_readlane_b32 s0, v250, 57
	v_mov_b32_e32 v6, v179
	v_readlane_b32 s1, v250, 58
	s_waitcnt lgkmcnt(0)
	s_barrier
	s_andn2_b64 vcc, exec, s[0:1]
	v_readfirstlane_b32 s0, v6
	s_cbranch_vccnz .LBB0_368
	v_readfirstlane_b32 s100, v179
	s_lshr_b32 s100, s100, 6
	s_cmp_ge_u32 s100, 4
	s_cbranch_scc0 .Lprio_done2
	s_setprio 1
.Lprio_done2:
	v_lshlrev_b32_e32 v3, 4, v6
	v_add_u32_e32 v1, 0x2000, v3
	v_ashrrev_i32_e32 v0, 31, v1
	v_lshrrev_b32_e32 v0, 22, v0
	v_add_u32_e32 v0, v1, v0
	v_ashrrev_i32_e32 v0, 10, v0
	v_mul_i32_i24_e32 v2, 0x400, v0
	v_sub_u32_e32 v1, v1, v2
	v_lshrrev_b32_e32 v2, 4, v1
	v_bitop3_b32 v2, v2, v1, 32 bitop3:0x6c
	v_ashrrev_i32_e32 v1, 31, v2
	v_lshrrev_b32_e32 v1, 26, v1
	v_add_u32_e32 v4, v2, v1
	v_lshlrev_b32_e32 v5, 3, v0
	v_ashrrev_i32_e32 v1, 6, v4
	v_and_b32_e32 v5, -16, v5
	v_add_u32_e32 v5, v1, v5
	v_and_b32_e32 v7, 3, v1
	s_mov_b32 s4, 0x1fffe0
	v_lshrrev_b32_e32 v8, 2, v5
	v_lshlrev_b32_e32 v9, 1, v5
	v_and_b32_e32 v4, 0xc0, v4
	v_and_or_b32 v7, v5, s4, v7
	v_and_b32_e32 v8, 4, v8
	v_and_b32_e32 v9, 24, v9
	v_sub_u32_e32 v2, v2, v4
	v_or3_b32 v7, v7, v8, v9
	v_lshlrev_b32_e32 v8, 5, v0
	v_ashrrev_i16_sdwa v2, v213, sext(v2) dst_sel:DWORD dst_unused:UNUSED_PAD src0_sel:DWORD src1_sel:BYTE_0
	v_and_b32_e32 v8, 32, v8
	v_bfe_i32 v2, v2, 0, 16
	v_add_lshl_u32 v4, v8, v2, 1
	v_lshl_add_u32 v128, v7, 11, v4
	v_lshl_add_u32 v130, v5, 11, v4
	v_bfe_i32 v4, v6, 27, 1
	v_lshrrev_b32_e32 v4, 22, v4
	v_add_u32_e32 v4, v3, v4
	v_and_b32_e32 v4, 0xfffffc00, v4
	v_sub_u32_e32 v3, v3, v4
	v_lshrrev_b32_e32 v4, 4, v3
	v_bitop3_b32 v5, v4, v3, 32 bitop3:0x6c
	v_ashrrev_i32_e32 v4, 31, v6
	v_lshrrev_b32_e32 v4, 26, v4
	v_ashrrev_i32_e32 v3, 31, v3
	v_add_u32_e32 v4, v6, v4
	v_lshrrev_b32_e32 v3, 26, v3
	v_ashrrev_i32_e32 v4, 6, v4
	v_add_u32_e32 v3, v5, v3
	v_lshlrev_b32_e32 v7, 3, v4
	v_ashrrev_i32_e32 v3, 6, v3
	v_and_b32_e32 v7, -16, v7
	v_add_u32_e32 v7, v3, v7
	v_and_b32_e32 v8, 3, v3
	v_lshrrev_b32_e32 v9, 2, v7
	v_lshlrev_b32_e32 v10, 1, v7
	v_and_or_b32 v8, v7, s4, v8
	v_and_b32_e32 v9, 4, v9
	v_and_b32_e32 v10, 24, v10
	v_or3_b32 v8, v8, v9, v10
	v_mul_i32_i24_e32 v10, 64, v3
	v_sub_u32_e32 v5, v5, v10
	s_ashr_i32 s1, s0, 6
	v_lshlrev_b32_e32 v9, 5, v4
	v_ashrrev_i16_sdwa v5, v213, sext(v5) dst_sel:DWORD dst_unused:UNUSED_PAD src0_sel:DWORD src1_sel:BYTE_0
	s_lshl_b32 s40, s1, 10
	v_and_b32_e32 v9, 32, v9
	v_bfe_i32 v5, v5, 0, 16
	v_add_lshl_u32 v9, v9, v5, 1
	s_add_i32 s41, s40, 0
	v_readlane_b32 s4, v252, 15
	v_lshl_add_u32 v156, v8, 11, v9
	s_add_i32 m0, s41, 0x10000
	v_readlane_b32 s5, v252, 16
	v_lshl_add_u32 v132, v7, 11, v9
	s_add_i32 s44, s41, 0x2000
	s_add_i32 s46, s41, 0x4000
	s_add_i32 s47, s41, 0x6000
	s_ashr_i32 s6, s0, 8
	global_load_lds_dwordx4 v156, s[4:5]
	s_add_i32 m0, s41, 0x12000
	s_nop 0
	global_load_lds_dwordx4 v128, s[4:5]
	v_readlane_b32 s4, v252, 9
	s_add_i32 m0, s41, 0x14000
	v_readlane_b32 s5, v252, 10
	s_nop 4
	global_load_lds_dwordx4 v156, s[4:5]
	s_add_i32 m0, s41, 0x16000
	s_cmp_eq_u32 s6, 1
	global_load_lds_dwordx4 v128, s[4:5]
	v_readlane_b32 s4, v252, 11
	s_mov_b32 m0, s41
	v_readlane_b32 s5, v252, 12
	s_nop 4
	global_load_lds_dwordx4 v132, s[4:5]
	s_mov_b32 m0, s44
	s_nop 0
	global_load_lds_dwordx4 v130, s[4:5]
	v_readlane_b32 s4, v252, 13
	s_mov_b32 m0, s46
	v_readlane_b32 s5, v252, 14
	s_nop 4
	global_load_lds_dwordx4 v132, s[4:5]
	s_mov_b32 m0, s47
	s_nop 0
	global_load_lds_dwordx4 v130, s[4:5]
	s_cselect_b64 s[4:5], -1, 0
	s_cmp_lg_u32 s6, 1
	s_cbranch_scc1 .LBB0_355
	s_barrier

.LBB0_361:
	s_add_u32 s18, s16, 0xfffc0080
	s_addc_u32 s19, s17, -1
	s_add_i32 s72, 0, 0x10000
	s_cmp_eq_u32 s59, 12
	s_cselect_b32 s23, s11, s19
	s_cselect_b32 s22, s53, s18
	v_add_u32_e32 v154, s72, v139
	s_cselect_b32 s19, s9, s58
	s_cselect_b32 s18, s54, s55
	s_add_i32 s86, 0, 0x14000
	ds_read_b128 v[142:145], v154
	ds_read_b128 v[146:149], v154 offset:1024
	ds_read_b128 v[150:153], v154 offset:2048
	ds_read_b128 v[172:175], v154 offset:3072
	v_add_u32_e32 v154, s86, v139
	ds_read_b128 v[180:183], v154
	ds_read_b128 v[184:187], v154 offset:1024
	ds_read_b128 v[188:191], v154 offset:2048
	ds_read_b128 v[192:195], v154 offset:3072
	v_lshl_add_u64 v[154:155], s[16:17], 0, v[134:135]
	s_add_i32 m0, s41, 0xc000
	ds_read_b128 v[196:199], v141
	ds_read_b128 v[200:203], v141 offset:1024
	ds_read_b128 v[204:207], v141 offset:2048
	ds_read_b128 v[208:211], v141 offset:3072
	ds_read_b128 v[226:229], v141 offset:4096
	ds_read_b128 v[230:233], v141 offset:5120
	ds_read_b128 v[234:237], v141 offset:6144
	ds_read_b128 v[238:241], v141 offset:7168
	global_load_lds_dwordx4 v[154:155], off
	v_lshl_add_u64 v[154:155], s[16:17], 0, v[136:137]
	s_add_i32 m0, s41, 0xe000
	s_nop 0
	global_load_lds_dwordx4 v[154:155], off
	s_waitcnt vmcnt(8)
	s_waitcnt lgkmcnt(0)
	s_barrier
	s_waitcnt lgkmcnt(0)
	v_mfma_f32_16x16x32_bf16 v[124:127], v[142:145], v[196:199], v[124:127]
	v_mfma_f32_16x16x32_bf16 v[120:123], v[150:153], v[196:199], v[120:123]
	v_mfma_f32_16x16x32_bf16 v[116:119], v[142:145], v[204:207], v[116:119]
	v_mfma_f32_16x16x32_bf16 v[112:115], v[150:153], v[204:207], v[112:115]
	v_mfma_f32_16x16x32_bf16 v[100:103], v[142:145], v[226:229], v[100:103]
	v_mfma_f32_16x16x32_bf16 v[96:99], v[150:153], v[226:229], v[96:99]
	v_mfma_f32_16x16x32_bf16 v[84:87], v[142:145], v[234:237], v[84:87]
	v_mfma_f32_16x16x32_bf16 v[80:83], v[150:153], v[234:237], v[80:83]
	v_mfma_f32_16x16x32_bf16 v[124:127], v[146:149], v[200:203], v[124:127]
	v_mfma_f32_16x16x32_bf16 v[120:123], v[172:175], v[200:203], v[120:123]
	v_mfma_f32_16x16x32_bf16 v[116:119], v[146:149], v[208:211], v[116:119]
	v_mfma_f32_16x16x32_bf16 v[112:115], v[172:175], v[208:211], v[112:115]
	v_mfma_f32_16x16x32_bf16 v[100:103], v[146:149], v[230:233], v[100:103]
	v_mfma_f32_16x16x32_bf16 v[96:99], v[172:175], v[230:233], v[96:99]
	v_mfma_f32_16x16x32_bf16 v[84:87], v[146:149], v[238:241], v[84:87]
	v_mfma_f32_16x16x32_bf16 v[80:83], v[172:175], v[238:241], v[80:83]
	v_mfma_f32_16x16x32_bf16 v[108:111], v[180:183], v[196:199], v[108:111]
	v_mfma_f32_16x16x32_bf16 v[104:107], v[188:191], v[196:199], v[104:107]
	v_mfma_f32_16x16x32_bf16 v[92:95], v[180:183], v[204:207], v[92:95]
	v_mfma_f32_16x16x32_bf16 v[88:91], v[188:191], v[204:207], v[88:91]
	v_mfma_f32_16x16x32_bf16 v[76:79], v[180:183], v[226:229], v[76:79]
	v_mfma_f32_16x16x32_bf16 v[72:75], v[188:191], v[226:229], v[72:75]
	v_mfma_f32_16x16x32_bf16 v[68:71], v[180:183], v[234:237], v[68:71]
	v_mfma_f32_16x16x32_bf16 v[64:67], v[188:191], v[234:237], v[64:67]
	v_mfma_f32_16x16x32_bf16 v[108:111], v[184:187], v[200:203], v[108:111]
	v_mfma_f32_16x16x32_bf16 v[104:107], v[192:195], v[200:203], v[104:107]
	v_mfma_f32_16x16x32_bf16 v[92:95], v[184:187], v[208:211], v[92:95]
	v_mfma_f32_16x16x32_bf16 v[88:91], v[192:195], v[208:211], v[88:91]
	v_mfma_f32_16x16x32_bf16 v[76:79], v[184:187], v[230:233], v[76:79]
	v_mfma_f32_16x16x32_bf16 v[72:75], v[192:195], v[230:233], v[72:75]
	v_mfma_f32_16x16x32_bf16 v[68:71], v[184:187], v[238:241], v[68:71]
	v_mfma_f32_16x16x32_bf16 v[64:67], v[192:195], v[238:241], v[64:67]
	s_barrier
	s_add_i32 s72, s72, s40
	v_lshl_add_u64 v[154:155], s[18:19], 0, v[156:157]
	s_mov_b32 m0, s72
	ds_read_b128 v[196:199], v141 offset:16384
	ds_read_b128 v[200:203], v141 offset:17408
	ds_read_b128 v[204:207], v141 offset:18432
	ds_read_b128 v[208:211], v141 offset:19456
	ds_read_b128 v[226:229], v141 offset:20480
	ds_read_b128 v[230:233], v141 offset:21504
	ds_read_b128 v[234:237], v141 offset:22528
	ds_read_b128 v[238:241], v141 offset:23552
	global_load_lds_dwordx4 v[154:155], off
	s_add_i32 m0, s72, 0x2000
	s_add_u32 s72, s18, 0x40000
	v_lshl_add_u64 v[176:177], s[18:19], 0, v[128:129]
	s_addc_u32 s73, s19, 0
	s_add_i32 s86, s86, s40
	global_load_lds_dwordx4 v[176:177], off
	v_lshl_add_u64 v[242:243], s[72:73], 0, v[156:157]
	s_mov_b32 m0, s86
	v_lshl_add_u64 v[244:245], s[22:23], 0, v[130:131]
	global_load_lds_dwordx4 v[242:243], off
	v_lshl_add_u64 v[242:243], s[72:73], 0, v[128:129]
	s_add_i32 m0, s86, 0x2000
	s_nop 0
	global_load_lds_dwordx4 v[242:243], off
	v_lshl_add_u64 v[242:243], s[22:23], 0, v[132:133]
	s_mov_b32 m0, s41
	s_nop 0
	global_load_lds_dwordx4 v[242:243], off
	s_mov_b32 m0, s44
	s_nop 0
	global_load_lds_dwordx4 v[244:245], off
	s_waitcnt vmcnt(8)
	s_waitcnt lgkmcnt(0)
	s_barrier
	s_waitcnt lgkmcnt(0)
	v_mfma_f32_16x16x32_bf16 v[60:63], v[142:145], v[196:199], v[60:63]
	v_mfma_f32_16x16x32_bf16 v[56:59], v[150:153], v[196:199], v[56:59]
	v_mfma_f32_16x16x32_bf16 v[52:55], v[142:145], v[204:207], v[52:55]
	v_mfma_f32_16x16x32_bf16 v[48:51], v[150:153], v[204:207], v[48:51]
	v_mfma_f32_16x16x32_bf16 v[36:39], v[142:145], v[226:229], v[36:39]
	v_mfma_f32_16x16x32_bf16 v[32:35], v[150:153], v[226:229], v[32:35]
	v_mfma_f32_16x16x32_bf16 v[20:23], v[142:145], v[234:237], v[20:23]
	v_mfma_f32_16x16x32_bf16 v[16:19], v[150:153], v[234:237], v[16:19]
	v_mfma_f32_16x16x32_bf16 v[60:63], v[146:149], v[200:203], v[60:63]
	v_mfma_f32_16x16x32_bf16 v[56:59], v[172:175], v[200:203], v[56:59]
	v_mfma_f32_16x16x32_bf16 v[52:55], v[146:149], v[208:211], v[52:55]
	v_mfma_f32_16x16x32_bf16 v[48:51], v[172:175], v[208:211], v[48:51]
	v_mfma_f32_16x16x32_bf16 v[36:39], v[146:149], v[230:233], v[36:39]
	v_mfma_f32_16x16x32_bf16 v[32:35], v[172:175], v[230:233], v[32:35]
	v_mfma_f32_16x16x32_bf16 v[20:23], v[146:149], v[238:241], v[20:23]
	v_mfma_f32_16x16x32_bf16 v[16:19], v[172:175], v[238:241], v[16:19]
	v_mfma_f32_16x16x32_bf16 v[44:47], v[180:183], v[196:199], v[44:47]
	v_mfma_f32_16x16x32_bf16 v[40:43], v[188:191], v[196:199], v[40:43]
	v_mfma_f32_16x16x32_bf16 v[28:31], v[180:183], v[204:207], v[28:31]
	v_mfma_f32_16x16x32_bf16 v[24:27], v[188:191], v[204:207], v[24:27]
	v_mfma_f32_16x16x32_bf16 v[12:15], v[180:183], v[226:229], v[12:15]
	v_mfma_f32_16x16x32_bf16 v[8:11], v[188:191], v[226:229], v[8:11]
	v_mfma_f32_16x16x32_bf16 v[4:7], v[180:183], v[234:237], v[4:7]
	v_mfma_f32_16x16x32_bf16 v[0:3], v[188:191], v[234:237], v[0:3]
	v_mfma_f32_16x16x32_bf16 v[44:47], v[184:187], v[200:203], v[44:47]
	v_mfma_f32_16x16x32_bf16 v[40:43], v[192:195], v[200:203], v[40:43]
	v_mfma_f32_16x16x32_bf16 v[28:31], v[184:187], v[208:211], v[28:31]
	v_mfma_f32_16x16x32_bf16 v[24:27], v[192:195], v[208:211], v[24:27]
	v_mfma_f32_16x16x32_bf16 v[12:15], v[184:187], v[230:233], v[12:15]
	v_mfma_f32_16x16x32_bf16 v[8:11], v[192:195], v[230:233], v[8:11]
	v_mfma_f32_16x16x32_bf16 v[4:7], v[184:187], v[238:241], v[4:7]
	v_mfma_f32_16x16x32_bf16 v[0:3], v[192:195], v[238:241], v[0:3]
	s_barrier
	s_add_i32 s72, 0, 0x18000
	s_add_i32 s73, 0, 0x1c000
	v_add_u32_e32 v172, s72, v139
	v_add_u32_e32 v178, s73, v139
	ds_read_b128 v[142:145], v172
	ds_read_b128 v[146:149], v172 offset:1024
	ds_read_b128 v[150:153], v172 offset:2048
	ds_read_b128 v[172:175], v172 offset:3072
	ds_read_b128 v[180:183], v178
	ds_read_b128 v[184:187], v178 offset:1024
	ds_read_b128 v[188:191], v178 offset:2048
	ds_read_b128 v[192:195], v178 offset:3072
	s_add_u32 s22, s22, 0x40000
	s_addc_u32 s23, s23, 0
	s_mov_b32 m0, s46
	v_lshl_add_u64 v[246:247], s[22:23], 0, v[132:133]
	ds_read_b128 v[196:199], v141 offset:32768
	ds_read_b128 v[200:203], v141 offset:33792
	ds_read_b128 v[204:207], v141 offset:34816
	ds_read_b128 v[208:211], v141 offset:35840
	ds_read_b128 v[226:229], v141 offset:36864
	ds_read_b128 v[230:233], v141 offset:37888
	ds_read_b128 v[234:237], v141 offset:38912
	ds_read_b128 v[238:241], v141 offset:39936
	global_load_lds_dwordx4 v[246:247], off
	v_lshl_add_u64 v[246:247], s[22:23], 0, v[130:131]
	s_mov_b32 m0, s47
	s_nop 0
	global_load_lds_dwordx4 v[246:247], off
	s_waitcnt vmcnt(8)
	s_waitcnt lgkmcnt(0)
	s_barrier
	s_waitcnt lgkmcnt(0)
	v_mfma_f32_16x16x32_bf16 v[124:127], v[142:145], v[196:199], v[124:127]
	v_mfma_f32_16x16x32_bf16 v[120:123], v[150:153], v[196:199], v[120:123]
	v_mfma_f32_16x16x32_bf16 v[116:119], v[142:145], v[204:207], v[116:119]
	v_mfma_f32_16x16x32_bf16 v[112:115], v[150:153], v[204:207], v[112:115]
	v_mfma_f32_16x16x32_bf16 v[100:103], v[142:145], v[226:229], v[100:103]
	v_mfma_f32_16x16x32_bf16 v[96:99], v[150:153], v[226:229], v[96:99]
	v_mfma_f32_16x16x32_bf16 v[84:87], v[142:145], v[234:237], v[84:87]
	v_mfma_f32_16x16x32_bf16 v[80:83], v[150:153], v[234:237], v[80:83]
	v_mfma_f32_16x16x32_bf16 v[124:127], v[146:149], v[200:203], v[124:127]
	v_mfma_f32_16x16x32_bf16 v[120:123], v[172:175], v[200:203], v[120:123]
	v_mfma_f32_16x16x32_bf16 v[116:119], v[146:149], v[208:211], v[116:119]
	v_mfma_f32_16x16x32_bf16 v[112:115], v[172:175], v[208:211], v[112:115]
	v_mfma_f32_16x16x32_bf16 v[100:103], v[146:149], v[230:233], v[100:103]
	v_mfma_f32_16x16x32_bf16 v[96:99], v[172:175], v[230:233], v[96:99]
	v_mfma_f32_16x16x32_bf16 v[84:87], v[146:149], v[238:241], v[84:87]
	v_mfma_f32_16x16x32_bf16 v[80:83], v[172:175], v[238:241], v[80:83]
	v_mfma_f32_16x16x32_bf16 v[108:111], v[180:183], v[196:199], v[108:111]
	v_mfma_f32_16x16x32_bf16 v[104:107], v[188:191], v[196:199], v[104:107]
	v_mfma_f32_16x16x32_bf16 v[92:95], v[180:183], v[204:207], v[92:95]
	v_mfma_f32_16x16x32_bf16 v[88:91], v[188:191], v[204:207], v[88:91]
	v_mfma_f32_16x16x32_bf16 v[76:79], v[180:183], v[226:229], v[76:79]
	v_mfma_f32_16x16x32_bf16 v[72:75], v[188:191], v[226:229], v[72:75]
	v_mfma_f32_16x16x32_bf16 v[68:71], v[180:183], v[234:237], v[68:71]
	v_mfma_f32_16x16x32_bf16 v[64:67], v[188:191], v[234:237], v[64:67]
	v_mfma_f32_16x16x32_bf16 v[108:111], v[184:187], v[200:203], v[108:111]
	v_mfma_f32_16x16x32_bf16 v[104:107], v[192:195], v[200:203], v[104:107]
	v_mfma_f32_16x16x32_bf16 v[92:95], v[184:187], v[208:211], v[92:95]
	v_mfma_f32_16x16x32_bf16 v[88:91], v[192:195], v[208:211], v[88:91]
	v_mfma_f32_16x16x32_bf16 v[76:79], v[184:187], v[230:233], v[76:79]
	v_mfma_f32_16x16x32_bf16 v[72:75], v[192:195], v[230:233], v[72:75]
	v_mfma_f32_16x16x32_bf16 v[68:71], v[184:187], v[238:241], v[68:71]
	v_mfma_f32_16x16x32_bf16 v[64:67], v[192:195], v[238:241], v[64:67]
	s_barrier
	s_add_i32 s22, s72, s40
	v_lshl_add_u64 v[154:155], v[154:155], 0, s[64:65]
	s_mov_b32 m0, s22
	ds_read_b128 v[196:199], v141 offset:49152
	ds_read_b128 v[200:203], v141 offset:50176
	ds_read_b128 v[204:207], v141 offset:51200
	ds_read_b128 v[208:211], v141 offset:52224
	ds_read_b128 v[226:229], v141 offset:53248
	ds_read_b128 v[230:233], v141 offset:54272
	ds_read_b128 v[234:237], v141 offset:55296
	ds_read_b128 v[238:241], v141 offset:56320
	global_load_lds_dwordx4 v[154:155], off
	s_add_i32 m0, s22, 0x2000
	s_add_u32 s18, s18, 0x40080
	v_lshl_add_u64 v[154:155], v[176:177], 0, s[64:65]
	s_addc_u32 s19, s19, 0
	s_add_i32 s22, s73, s40
	global_load_lds_dwordx4 v[154:155], off
	v_lshl_add_u64 v[154:155], s[18:19], 0, v[156:157]
	s_mov_b32 m0, s22
	s_nop 0
	global_load_lds_dwordx4 v[154:155], off
	v_lshl_add_u64 v[154:155], s[18:19], 0, v[128:129]
	s_add_i32 m0, s22, 0x2000
	s_nop 0
	global_load_lds_dwordx4 v[154:155], off
	v_lshl_add_u64 v[154:155], v[242:243], 0, s[64:65]
	s_mov_b32 m0, s48
	s_nop 0
	global_load_lds_dwordx4 v[154:155], off
	v_lshl_add_u64 v[154:155], v[244:245], 0, s[64:65]
	s_mov_b32 m0, s49
	s_nop 0
	global_load_lds_dwordx4 v[154:155], off
	s_waitcnt vmcnt(8)
	s_waitcnt lgkmcnt(0)
	s_barrier
	s_waitcnt lgkmcnt(0)
	v_mfma_f32_16x16x32_bf16 v[60:63], v[142:145], v[196:199], v[60:63]
	v_mfma_f32_16x16x32_bf16 v[56:59], v[150:153], v[196:199], v[56:59]
	v_mfma_f32_16x16x32_bf16 v[52:55], v[142:145], v[204:207], v[52:55]
	v_mfma_f32_16x16x32_bf16 v[48:51], v[150:153], v[204:207], v[48:51]
	v_mfma_f32_16x16x32_bf16 v[36:39], v[142:145], v[226:229], v[36:39]
	v_mfma_f32_16x16x32_bf16 v[32:35], v[150:153], v[226:229], v[32:35]
	v_mfma_f32_16x16x32_bf16 v[20:23], v[142:145], v[234:237], v[20:23]
	v_mfma_f32_16x16x32_bf16 v[16:19], v[150:153], v[234:237], v[16:19]
	v_mfma_f32_16x16x32_bf16 v[60:63], v[146:149], v[200:203], v[60:63]
	v_mfma_f32_16x16x32_bf16 v[56:59], v[172:175], v[200:203], v[56:59]
	v_mfma_f32_16x16x32_bf16 v[52:55], v[146:149], v[208:211], v[52:55]
	v_mfma_f32_16x16x32_bf16 v[48:51], v[172:175], v[208:211], v[48:51]
	v_mfma_f32_16x16x32_bf16 v[36:39], v[146:149], v[230:233], v[36:39]
	v_mfma_f32_16x16x32_bf16 v[32:35], v[172:175], v[230:233], v[32:35]
	v_mfma_f32_16x16x32_bf16 v[20:23], v[146:149], v[238:241], v[20:23]
	v_mfma_f32_16x16x32_bf16 v[16:19], v[172:175], v[238:241], v[16:19]
	v_mfma_f32_16x16x32_bf16 v[44:47], v[180:183], v[196:199], v[44:47]
	v_mfma_f32_16x16x32_bf16 v[40:43], v[188:191], v[196:199], v[40:43]
	v_mfma_f32_16x16x32_bf16 v[28:31], v[180:183], v[204:207], v[28:31]
	v_mfma_f32_16x16x32_bf16 v[24:27], v[188:191], v[204:207], v[24:27]
	v_mfma_f32_16x16x32_bf16 v[12:15], v[180:183], v[226:229], v[12:15]
	v_mfma_f32_16x16x32_bf16 v[8:11], v[188:191], v[226:229], v[8:11]
	v_mfma_f32_16x16x32_bf16 v[4:7], v[180:183], v[234:237], v[4:7]
	v_mfma_f32_16x16x32_bf16 v[0:3], v[188:191], v[234:237], v[0:3]
	v_mfma_f32_16x16x32_bf16 v[44:47], v[184:187], v[200:203], v[44:47]
	v_mfma_f32_16x16x32_bf16 v[40:43], v[192:195], v[200:203], v[40:43]
	v_mfma_f32_16x16x32_bf16 v[28:31], v[184:187], v[208:211], v[28:31]
	v_mfma_f32_16x16x32_bf16 v[24:27], v[192:195], v[208:211], v[24:27]
	v_mfma_f32_16x16x32_bf16 v[12:15], v[184:187], v[230:233], v[12:15]
	v_mfma_f32_16x16x32_bf16 v[8:11], v[192:195], v[230:233], v[8:11]
	v_mfma_f32_16x16x32_bf16 v[4:7], v[184:187], v[238:241], v[4:7]
	v_mfma_f32_16x16x32_bf16 v[0:3], v[192:195], v[238:241], v[0:3]
	s_barrier
	s_add_i32 s59, s59, 2
	s_add_u32 s16, s16, 0x100
	s_addc_u32 s17, s17, 0
	s_add_u32 s55, s55, 0x100
	s_addc_u32 s58, s58, 0
	s_cmp_gt_u32 s59, 13
	s_cbranch_scc0 .LBB0_361
	s_and_b64 vcc, exec, s[6:7]
	s_cbranch_vccz .LBB0_364
	s_barrier

.LBB0_957:
	s_or_b64 exec, exec, s[0:1]
	v_mov_b32_e32 v8, v179
	s_waitcnt lgkmcnt(0)
	s_barrier
	s_and_b64 vcc, exec, s[74:75]
	v_readfirstlane_b32 s0, v8
	s_cbranch_vccnz .LBB0_977
	v_readfirstlane_b32 s100, v179
	s_lshr_b32 s100, s100, 6
	s_cmp_ge_u32 s100, 4
	s_cbranch_scc0 .Lprio_done3
	s_setprio 1
.Lprio_done3:
	v_lshlrev_b32_e32 v4, 4, v8
	v_add_u32_e32 v1, 0x2000, v4
	v_ashrrev_i32_e32 v0, 31, v1
	v_lshrrev_b32_e32 v0, 22, v0
	v_add_u32_e32 v0, v1, v0
	v_ashrrev_i32_e32 v0, 10, v0
	v_mul_i32_i24_e32 v2, 0x400, v0
	v_sub_u32_e32 v1, v1, v2
	v_lshrrev_b32_e32 v2, 4, v1
	v_bitop3_b32 v3, v2, v1, 32 bitop3:0x6c
	v_ashrrev_i32_e32 v1, 31, v3
	v_lshrrev_b32_e32 v1, 26, v1
	v_add_u32_e32 v5, v3, v1
	v_ashrrev_i32_e32 v1, 6, v5
	v_and_b32_e32 v5, 0xc0, v5
	v_sub_u32_e32 v3, v3, v5
	v_bfe_i32 v5, v8, 27, 1
	v_lshrrev_b32_e32 v5, 22, v5
	v_add_u32_e32 v5, v4, v5
	v_and_b32_e32 v5, 0xfffffc00, v5
	v_sub_u32_e32 v4, v4, v5
	v_lshlrev_b32_e32 v2, 3, v0
	v_lshrrev_b32_e32 v5, 4, v4
	v_and_b32_e32 v2, 0x1ffff0, v2
	v_bitop3_b32 v7, v5, v4, 32 bitop3:0x6c
	v_ashrrev_i32_e32 v5, 31, v8
	v_add_u32_e32 v6, v1, v2
	v_lshlrev_b32_e32 v2, 5, v0
	v_ashrrev_i32_e32 v4, 31, v4
	v_lshrrev_b32_e32 v5, 26, v5
	v_and_b32_e32 v2, 32, v2
	v_ashrrev_i16_sdwa v3, v213, sext(v3) dst_sel:DWORD dst_unused:UNUSED_PAD src0_sel:DWORD src1_sel:BYTE_0
	v_lshrrev_b32_e32 v4, 26, v4
	v_add_u32_e32 v5, v8, v5
	v_lshl_or_b32 v6, v6, 10, v2
	v_bfe_i32 v3, v3, 0, 16
	v_add_u32_e32 v4, v7, v4
	v_ashrrev_i32_e32 v5, 6, v5
	v_add_lshl_u32 v144, v6, v3, 1
	v_ashrrev_i32_e32 v4, 6, v4
	v_lshlrev_b32_e32 v6, 3, v5
	v_and_b32_e32 v6, 0x1ffff0, v6
	v_mul_i32_i24_e32 v10, 64, v4
	s_ashr_i32 s1, s0, 6
	v_add_u32_e32 v9, v4, v6
	v_lshlrev_b32_e32 v6, 5, v5
	v_sub_u32_e32 v7, v7, v10
	s_lshl_b32 s44, s1, 10
	v_and_b32_e32 v6, 32, v6
	v_ashrrev_i16_sdwa v7, v213, sext(v7) dst_sel:DWORD dst_unused:UNUSED_PAD src0_sel:DWORD src1_sel:BYTE_0
	v_lshl_or_b32 v9, v9, 10, v6
	v_bfe_i32 v7, v7, 0, 16
	s_add_i32 s46, s44, 0
	v_readlane_b32 s4, v252, 27
	v_add_lshl_u32 v156, v9, v7, 1
	s_add_i32 m0, s46, 0x10000
	v_readlane_b32 s5, v252, 28
	s_add_i32 s47, s46, 0x2000
	s_add_i32 s48, s46, 0x4000
	s_add_i32 s49, s46, 0x6000
	s_ashr_i32 s6, s0, 8
	s_nop 0
	global_load_lds_dwordx4 v156, s[4:5]
	s_add_i32 m0, s46, 0x12000
	s_nop 0
	global_load_lds_dwordx4 v144, s[4:5]
	v_readlane_b32 s4, v252, 21
	s_add_i32 m0, s46, 0x14000
	v_readlane_b32 s5, v252, 22
	s_nop 4
	global_load_lds_dwordx4 v156, s[4:5]
	s_add_i32 m0, s46, 0x16000
	s_cmp_eq_u32 s6, 1
	global_load_lds_dwordx4 v144, s[4:5]
	v_readlane_b32 s4, v252, 23
	s_mov_b32 m0, s46
	v_readlane_b32 s5, v252, 24
	s_nop 4
	global_load_lds_dwordx4 v156, s[4:5]
	s_mov_b32 m0, s47
	s_nop 0
	global_load_lds_dwordx4 v144, s[4:5]
	v_readlane_b32 s4, v252, 25
	s_mov_b32 m0, s48
	v_readlane_b32 s5, v252, 26
	s_nop 4
	global_load_lds_dwordx4 v156, s[4:5]
	s_mov_b32 m0, s49
	s_nop 0
	global_load_lds_dwordx4 v144, s[4:5]
	s_cselect_b64 s[4:5], -1, 0
	s_cmp_lg_u32 s6, 1
	s_cbranch_scc1 .LBB0_960
	s_barrier

.LBB0_970:
	s_add_u32 s18, s16, 0x100
	s_addc_u32 s19, s17, 0
	s_add_i32 vcc_lo, 0, 0x10000
	s_cmp_eq_u32 s87, 12
	s_cselect_b32 s41, s11, s19
	s_cselect_b32 s40, s59, s18
	s_cselect_b32 s23, s9, s86
	s_cselect_b32 s22, s72, s73
	s_add_i32 vcc_hi, 0, 0x14000
	v_add_u32_e32 v104, vcc_lo, v155
	v_add_u32_e32 v178, vcc_hi, v155
	ds_read_b128 v[48:51], v104
	ds_read_b128 v[84:87], v104 offset:1024
	ds_read_b128 v[96:99], v104 offset:2048
	ds_read_b128 v[104:107], v104 offset:3072
	ds_read_b128 v[150:153], v178
	ds_read_b128 v[174:177], v178 offset:1024
	ds_read_b128 v[180:183], v178 offset:2048
	ds_read_b128 v[184:187], v178 offset:3072
	v_lshl_add_u64 v[234:235], s[16:17], 0, v[146:147]
	s_add_i32 m0, s46, 0xc000
	ds_read_b128 v[188:191], v173
	ds_read_b128 v[192:195], v173 offset:1024
	ds_read_b128 v[196:199], v173 offset:2048
	ds_read_b128 v[200:203], v173 offset:3072
	ds_read_b128 v[204:207], v173 offset:4096
	ds_read_b128 v[208:211], v173 offset:5120
	ds_read_b128 v[226:229], v173 offset:6144
	ds_read_b128 v[230:233], v173 offset:7168
	global_load_lds_dwordx4 v[234:235], off
	v_lshl_add_u64 v[234:235], s[16:17], 0, v[148:149]
	s_add_i32 m0, s46, 0xe000
	s_nop 0
	global_load_lds_dwordx4 v[234:235], off
	s_waitcnt vmcnt(8)
	s_waitcnt lgkmcnt(0)
	s_barrier
	s_waitcnt lgkmcnt(0)
	v_mfma_f32_16x16x32_bf16 v[140:143], v[48:51], v[188:191], v[140:143]
	v_mfma_f32_16x16x32_bf16 v[136:139], v[96:99], v[188:191], v[136:139]
	v_mfma_f32_16x16x32_bf16 v[124:127], v[48:51], v[196:199], v[124:127]
	v_mfma_f32_16x16x32_bf16 v[120:123], v[96:99], v[196:199], v[120:123]
	v_mfma_f32_16x16x32_bf16 v[108:111], v[48:51], v[204:207], v[108:111]
	v_mfma_f32_16x16x32_bf16 v[100:103], v[96:99], v[204:207], v[100:103]
	v_mfma_f32_16x16x32_bf16 v[80:83], v[48:51], v[226:229], v[80:83]
	v_mfma_f32_16x16x32_bf16 v[76:79], v[96:99], v[226:229], v[76:79]
	v_mfma_f32_16x16x32_bf16 v[140:143], v[84:87], v[192:195], v[140:143]
	v_mfma_f32_16x16x32_bf16 v[136:139], v[104:107], v[192:195], v[136:139]
	v_mfma_f32_16x16x32_bf16 v[124:127], v[84:87], v[200:203], v[124:127]
	v_mfma_f32_16x16x32_bf16 v[120:123], v[104:107], v[200:203], v[120:123]
	v_mfma_f32_16x16x32_bf16 v[108:111], v[84:87], v[208:211], v[108:111]
	v_mfma_f32_16x16x32_bf16 v[100:103], v[104:107], v[208:211], v[100:103]
	v_mfma_f32_16x16x32_bf16 v[80:83], v[84:87], v[230:233], v[80:83]
	v_mfma_f32_16x16x32_bf16 v[76:79], v[104:107], v[230:233], v[76:79]
	v_mfma_f32_16x16x32_bf16 v[132:135], v[150:153], v[188:191], v[132:135]
	v_mfma_f32_16x16x32_bf16 v[128:131], v[180:183], v[188:191], v[128:131]
	v_mfma_f32_16x16x32_bf16 v[116:119], v[150:153], v[196:199], v[116:119]
	v_mfma_f32_16x16x32_bf16 v[112:115], v[180:183], v[196:199], v[112:115]
	v_mfma_f32_16x16x32_bf16 v[92:95], v[150:153], v[204:207], v[92:95]
	v_mfma_f32_16x16x32_bf16 v[88:91], v[180:183], v[204:207], v[88:91]
	v_mfma_f32_16x16x32_bf16 v[72:75], v[150:153], v[226:229], v[72:75]
	v_mfma_f32_16x16x32_bf16 v[68:71], v[180:183], v[226:229], v[68:71]
	v_mfma_f32_16x16x32_bf16 v[132:135], v[174:177], v[192:195], v[132:135]
	v_mfma_f32_16x16x32_bf16 v[128:131], v[184:187], v[192:195], v[128:131]
	v_mfma_f32_16x16x32_bf16 v[116:119], v[174:177], v[200:203], v[116:119]
	v_mfma_f32_16x16x32_bf16 v[112:115], v[184:187], v[200:203], v[112:115]
	v_mfma_f32_16x16x32_bf16 v[92:95], v[174:177], v[208:211], v[92:95]
	v_mfma_f32_16x16x32_bf16 v[88:91], v[184:187], v[208:211], v[88:91]
	v_mfma_f32_16x16x32_bf16 v[72:75], v[174:177], v[230:233], v[72:75]
	v_mfma_f32_16x16x32_bf16 v[68:71], v[184:187], v[230:233], v[68:71]
	s_barrier
	s_add_i32 s16, vcc_lo, s44
	v_lshl_add_u64 v[234:235], s[22:23], 0, v[156:157]
	s_mov_b32 m0, s16
	ds_read_b128 v[188:191], v173 offset:16384
	ds_read_b128 v[192:195], v173 offset:17408
	ds_read_b128 v[196:199], v173 offset:18432
	ds_read_b128 v[200:203], v173 offset:19456
	ds_read_b128 v[204:207], v173 offset:20480
	ds_read_b128 v[208:211], v173 offset:21504
	ds_read_b128 v[226:229], v173 offset:22528
	ds_read_b128 v[230:233], v173 offset:23552
	global_load_lds_dwordx4 v[234:235], off
	s_add_i32 m0, s16, 0x2000
	s_add_u32 s16, s22, 0x40000
	v_lshl_add_u64 v[236:237], s[22:23], 0, v[144:145]
	s_addc_u32 s17, s23, 0
	s_add_i32 vcc_lo, vcc_hi, s44
	global_load_lds_dwordx4 v[236:237], off
	v_lshl_add_u64 v[238:239], s[16:17], 0, v[156:157]
	s_mov_b32 m0, vcc_lo
	v_lshl_add_u64 v[240:241], s[40:41], 0, v[144:145]
	global_load_lds_dwordx4 v[238:239], off
	v_lshl_add_u64 v[238:239], s[16:17], 0, v[144:145]
	s_add_i32 m0, vcc_lo, 0x2000
	s_nop 0
	global_load_lds_dwordx4 v[238:239], off
	v_lshl_add_u64 v[238:239], s[40:41], 0, v[156:157]
	s_mov_b32 m0, s46
	s_nop 0
	global_load_lds_dwordx4 v[238:239], off
	s_mov_b32 m0, s47
	s_nop 0
	global_load_lds_dwordx4 v[240:241], off
	s_waitcnt vmcnt(8)
	s_waitcnt lgkmcnt(0)
	s_barrier
	s_waitcnt lgkmcnt(0)
	v_mfma_f32_16x16x32_bf16 v[64:67], v[48:51], v[188:191], v[64:67]
	v_mfma_f32_16x16x32_bf16 v[60:63], v[96:99], v[188:191], v[60:63]
	v_mfma_f32_16x16x32_bf16 v[44:47], v[48:51], v[196:199], v[44:47]
	v_mfma_f32_16x16x32_bf16 v[40:43], v[96:99], v[196:199], v[40:43]
	v_mfma_f32_16x16x32_bf16 v[28:31], v[48:51], v[204:207], v[28:31]
	v_mfma_f32_16x16x32_bf16 v[24:27], v[96:99], v[204:207], v[24:27]
	v_mfma_f32_16x16x32_bf16 v[12:15], v[48:51], v[226:229], v[12:15]
	v_mfma_f32_16x16x32_bf16 v[8:11], v[96:99], v[226:229], v[8:11]
	v_mfma_f32_16x16x32_bf16 v[64:67], v[84:87], v[192:195], v[64:67]
	v_mfma_f32_16x16x32_bf16 v[60:63], v[104:107], v[192:195], v[60:63]
	v_mfma_f32_16x16x32_bf16 v[44:47], v[84:87], v[200:203], v[44:47]
	v_mfma_f32_16x16x32_bf16 v[40:43], v[104:107], v[200:203], v[40:43]
	v_mfma_f32_16x16x32_bf16 v[28:31], v[84:87], v[208:211], v[28:31]
	v_mfma_f32_16x16x32_bf16 v[24:27], v[104:107], v[208:211], v[24:27]
	v_mfma_f32_16x16x32_bf16 v[12:15], v[84:87], v[230:233], v[12:15]
	v_mfma_f32_16x16x32_bf16 v[8:11], v[104:107], v[230:233], v[8:11]
	v_mfma_f32_16x16x32_bf16 v[52:55], v[180:183], v[188:191], v[52:55]
	v_mfma_f32_16x16x32_bf16 v[36:39], v[150:153], v[196:199], v[36:39]
	v_mfma_f32_16x16x32_bf16 v[32:35], v[180:183], v[196:199], v[32:35]
	v_mfma_f32_16x16x32_bf16 v[20:23], v[150:153], v[204:207], v[20:23]
	v_mfma_f32_16x16x32_bf16 v[16:19], v[180:183], v[204:207], v[16:19]
	v_mfma_f32_16x16x32_bf16 v[4:7], v[150:153], v[226:229], v[4:7]
	v_mfma_f32_16x16x32_bf16 v[0:3], v[180:183], v[226:229], v[0:3]
	v_mfma_f32_16x16x32_bf16 v[48:51], v[150:153], v[188:191], v[56:59]
	v_mfma_f32_16x16x32_bf16 v[52:55], v[184:187], v[192:195], v[52:55]
	v_mfma_f32_16x16x32_bf16 v[36:39], v[174:177], v[200:203], v[36:39]
	v_mfma_f32_16x16x32_bf16 v[32:35], v[184:187], v[200:203], v[32:35]
	v_mfma_f32_16x16x32_bf16 v[20:23], v[174:177], v[208:211], v[20:23]
	v_mfma_f32_16x16x32_bf16 v[16:19], v[184:187], v[208:211], v[16:19]
	v_mfma_f32_16x16x32_bf16 v[4:7], v[174:177], v[230:233], v[4:7]
	v_mfma_f32_16x16x32_bf16 v[0:3], v[184:187], v[230:233], v[0:3]
	v_mfma_f32_16x16x32_bf16 v[48:51], v[174:177], v[192:195], v[48:51]
	s_barrier
	s_add_i32 vcc_lo, 0, 0x18000
	s_add_i32 vcc_hi, 0, 0x1c000
	v_add_u32_e32 v104, vcc_lo, v155
	v_add_u32_e32 v178, vcc_hi, v155
	ds_read_b128 v[56:59], v104
	ds_read_b128 v[84:87], v104 offset:1024
	ds_read_b128 v[96:99], v104 offset:2048
	ds_read_b128 v[104:107], v104 offset:3072
	ds_read_b128 v[150:153], v178
	ds_read_b128 v[174:177], v178 offset:1024
	ds_read_b128 v[180:183], v178 offset:2048
	ds_read_b128 v[184:187], v178 offset:3072
	s_add_u32 s16, s40, 0x40000
	s_addc_u32 s17, s41, 0
	s_mov_b32 m0, s48
	v_lshl_add_u64 v[242:243], s[16:17], 0, v[156:157]
	ds_read_b128 v[188:191], v173 offset:32768
	ds_read_b128 v[192:195], v173 offset:33792
	ds_read_b128 v[196:199], v173 offset:34816
	ds_read_b128 v[200:203], v173 offset:35840
	ds_read_b128 v[204:207], v173 offset:36864
	ds_read_b128 v[208:211], v173 offset:37888
	ds_read_b128 v[226:229], v173 offset:38912
	ds_read_b128 v[230:233], v173 offset:39936
	global_load_lds_dwordx4 v[242:243], off
	v_lshl_add_u64 v[242:243], s[16:17], 0, v[144:145]
	s_mov_b32 m0, s49
	s_nop 0
	global_load_lds_dwordx4 v[242:243], off
	s_waitcnt vmcnt(8)
	s_waitcnt lgkmcnt(0)
	s_barrier
	s_waitcnt lgkmcnt(0)
	v_mfma_f32_16x16x32_bf16 v[140:143], v[56:59], v[188:191], v[140:143]
	v_mfma_f32_16x16x32_bf16 v[136:139], v[96:99], v[188:191], v[136:139]
	v_mfma_f32_16x16x32_bf16 v[124:127], v[56:59], v[196:199], v[124:127]
	v_mfma_f32_16x16x32_bf16 v[120:123], v[96:99], v[196:199], v[120:123]
	v_mfma_f32_16x16x32_bf16 v[108:111], v[56:59], v[204:207], v[108:111]
	v_mfma_f32_16x16x32_bf16 v[100:103], v[96:99], v[204:207], v[100:103]
	v_mfma_f32_16x16x32_bf16 v[80:83], v[56:59], v[226:229], v[80:83]
	v_mfma_f32_16x16x32_bf16 v[76:79], v[96:99], v[226:229], v[76:79]
	v_mfma_f32_16x16x32_bf16 v[140:143], v[84:87], v[192:195], v[140:143]
	v_mfma_f32_16x16x32_bf16 v[136:139], v[104:107], v[192:195], v[136:139]
	v_mfma_f32_16x16x32_bf16 v[124:127], v[84:87], v[200:203], v[124:127]
	v_mfma_f32_16x16x32_bf16 v[120:123], v[104:107], v[200:203], v[120:123]
	v_mfma_f32_16x16x32_bf16 v[108:111], v[84:87], v[208:211], v[108:111]
	v_mfma_f32_16x16x32_bf16 v[100:103], v[104:107], v[208:211], v[100:103]
	v_mfma_f32_16x16x32_bf16 v[80:83], v[84:87], v[230:233], v[80:83]
	v_mfma_f32_16x16x32_bf16 v[76:79], v[104:107], v[230:233], v[76:79]
	v_mfma_f32_16x16x32_bf16 v[132:135], v[150:153], v[188:191], v[132:135]
	v_mfma_f32_16x16x32_bf16 v[128:131], v[180:183], v[188:191], v[128:131]
	v_mfma_f32_16x16x32_bf16 v[116:119], v[150:153], v[196:199], v[116:119]
	v_mfma_f32_16x16x32_bf16 v[112:115], v[180:183], v[196:199], v[112:115]
	v_mfma_f32_16x16x32_bf16 v[92:95], v[150:153], v[204:207], v[92:95]
	v_mfma_f32_16x16x32_bf16 v[88:91], v[180:183], v[204:207], v[88:91]
	v_mfma_f32_16x16x32_bf16 v[72:75], v[150:153], v[226:229], v[72:75]
	v_mfma_f32_16x16x32_bf16 v[68:71], v[180:183], v[226:229], v[68:71]
	v_mfma_f32_16x16x32_bf16 v[132:135], v[174:177], v[192:195], v[132:135]
	v_mfma_f32_16x16x32_bf16 v[128:131], v[184:187], v[192:195], v[128:131]
	v_mfma_f32_16x16x32_bf16 v[116:119], v[174:177], v[200:203], v[116:119]
	v_mfma_f32_16x16x32_bf16 v[112:115], v[184:187], v[200:203], v[112:115]
	v_mfma_f32_16x16x32_bf16 v[92:95], v[174:177], v[208:211], v[92:95]
	v_mfma_f32_16x16x32_bf16 v[88:91], v[184:187], v[208:211], v[88:91]
	v_mfma_f32_16x16x32_bf16 v[72:75], v[174:177], v[230:233], v[72:75]
	v_mfma_f32_16x16x32_bf16 v[68:71], v[184:187], v[230:233], v[68:71]
	s_barrier
	s_add_i32 s16, vcc_lo, s44
	v_lshl_add_u64 v[234:235], v[234:235], 0, s[64:65]
	s_mov_b32 m0, s16
	ds_read_b128 v[188:191], v173 offset:49152
	ds_read_b128 v[192:195], v173 offset:50176
	ds_read_b128 v[196:199], v173 offset:51200
	ds_read_b128 v[200:203], v173 offset:52224
	ds_read_b128 v[204:207], v173 offset:53248
	ds_read_b128 v[208:211], v173 offset:54272
	ds_read_b128 v[226:229], v173 offset:55296
	ds_read_b128 v[230:233], v173 offset:56320
	global_load_lds_dwordx4 v[234:235], off
	s_add_i32 m0, s16, 0x2000
	s_add_u32 s16, s22, 0x40080
	v_lshl_add_u64 v[234:235], v[236:237], 0, s[64:65]
	s_addc_u32 s17, s23, 0
	s_add_i32 s22, vcc_hi, s44
	global_load_lds_dwordx4 v[234:235], off
	v_lshl_add_u64 v[234:235], s[16:17], 0, v[156:157]
	s_mov_b32 m0, s22
	s_nop 0
	global_load_lds_dwordx4 v[234:235], off
	v_lshl_add_u64 v[234:235], s[16:17], 0, v[144:145]
	s_add_i32 m0, s22, 0x2000
	s_nop 0
	global_load_lds_dwordx4 v[234:235], off
	v_lshl_add_u64 v[234:235], v[238:239], 0, s[64:65]
	s_mov_b32 m0, s52
	s_nop 0
	global_load_lds_dwordx4 v[234:235], off
	v_lshl_add_u64 v[234:235], v[240:241], 0, s[64:65]
	s_mov_b32 m0, s53
	s_nop 0
	global_load_lds_dwordx4 v[234:235], off
	s_waitcnt vmcnt(8)
	s_waitcnt lgkmcnt(0)
	s_barrier
	s_waitcnt lgkmcnt(0)
	v_mfma_f32_16x16x32_bf16 v[64:67], v[56:59], v[188:191], v[64:67]
	v_mfma_f32_16x16x32_bf16 v[60:63], v[96:99], v[188:191], v[60:63]
	v_mfma_f32_16x16x32_bf16 v[44:47], v[56:59], v[196:199], v[44:47]
	v_mfma_f32_16x16x32_bf16 v[40:43], v[96:99], v[196:199], v[40:43]
	v_mfma_f32_16x16x32_bf16 v[28:31], v[56:59], v[204:207], v[28:31]
	v_mfma_f32_16x16x32_bf16 v[24:27], v[96:99], v[204:207], v[24:27]
	v_mfma_f32_16x16x32_bf16 v[12:15], v[56:59], v[226:229], v[12:15]
	v_mfma_f32_16x16x32_bf16 v[8:11], v[96:99], v[226:229], v[8:11]
	v_mfma_f32_16x16x32_bf16 v[64:67], v[84:87], v[192:195], v[64:67]
	v_mfma_f32_16x16x32_bf16 v[60:63], v[104:107], v[192:195], v[60:63]
	v_mfma_f32_16x16x32_bf16 v[44:47], v[84:87], v[200:203], v[44:47]
	v_mfma_f32_16x16x32_bf16 v[40:43], v[104:107], v[200:203], v[40:43]
	v_mfma_f32_16x16x32_bf16 v[28:31], v[84:87], v[208:211], v[28:31]
	v_mfma_f32_16x16x32_bf16 v[24:27], v[104:107], v[208:211], v[24:27]
	v_mfma_f32_16x16x32_bf16 v[12:15], v[84:87], v[230:233], v[12:15]
	v_mfma_f32_16x16x32_bf16 v[8:11], v[104:107], v[230:233], v[8:11]
	v_mfma_f32_16x16x32_bf16 v[48:51], v[150:153], v[188:191], v[48:51]
	v_mfma_f32_16x16x32_bf16 v[56:59], v[174:177], v[192:195], v[48:51]
	v_mfma_f32_16x16x32_bf16 v[48:51], v[180:183], v[188:191], v[52:55]
	v_mfma_f32_16x16x32_bf16 v[36:39], v[150:153], v[196:199], v[36:39]
	v_mfma_f32_16x16x32_bf16 v[32:35], v[180:183], v[196:199], v[32:35]
	v_mfma_f32_16x16x32_bf16 v[20:23], v[150:153], v[204:207], v[20:23]
	v_mfma_f32_16x16x32_bf16 v[16:19], v[180:183], v[204:207], v[16:19]
	v_mfma_f32_16x16x32_bf16 v[4:7], v[150:153], v[226:229], v[4:7]
	v_mfma_f32_16x16x32_bf16 v[0:3], v[180:183], v[226:229], v[0:3]
	v_mfma_f32_16x16x32_bf16 v[52:55], v[184:187], v[192:195], v[48:51]
	v_mfma_f32_16x16x32_bf16 v[36:39], v[174:177], v[200:203], v[36:39]
	v_mfma_f32_16x16x32_bf16 v[32:35], v[184:187], v[200:203], v[32:35]
	v_mfma_f32_16x16x32_bf16 v[20:23], v[174:177], v[208:211], v[20:23]
	v_mfma_f32_16x16x32_bf16 v[16:19], v[184:187], v[208:211], v[16:19]
	v_mfma_f32_16x16x32_bf16 v[4:7], v[174:177], v[230:233], v[4:7]
	v_mfma_f32_16x16x32_bf16 v[0:3], v[184:187], v[230:233], v[0:3]
	s_barrier
	s_add_i32 s87, s87, 2
	s_add_u32 s73, s73, 0x100
	s_addc_u32 s86, s86, 0
	s_cmp_gt_u32 s87, 13
	s_mov_b64 s[16:17], s[18:19]
	s_cbranch_scc0 .LBB0_970
	s_and_b64 vcc, exec, s[6:7]
	s_mov_b32 s87, 0x9000
	s_movk_i32 s86, 0x4000
	s_movk_i32 s72, 0x2000
	s_mov_b32 s73, 0x14000
	s_cbranch_vccz .LBB0_973
	s_barrier

.LBB0_1087:
	s_or_b64 exec, exec, s[0:1]
	v_readlane_b32 s0, v253, 30
	v_mov_b32_e32 v6, v179
	v_readlane_b32 s1, v253, 31
	s_waitcnt lgkmcnt(0)
	s_barrier
	s_and_b64 vcc, exec, s[0:1]
	v_readfirstlane_b32 s0, v6
	s_cbranch_vccnz .LBB0_1103
	v_readfirstlane_b32 s100, v179
	s_lshr_b32 s100, s100, 6
	s_cmp_ge_u32 s100, 4
	s_cbranch_scc0 .Lprio_done4
	s_setprio 1
.Lprio_done4:
	v_lshlrev_b32_e32 v3, 4, v6
	v_add_u32_e32 v1, 0x2000, v3
	v_ashrrev_i32_e32 v0, 31, v1
	v_lshrrev_b32_e32 v0, 22, v0
	v_add_u32_e32 v0, v1, v0
	v_ashrrev_i32_e32 v0, 10, v0
	v_mul_i32_i24_e32 v2, 0x400, v0
	v_sub_u32_e32 v1, v1, v2
	v_lshrrev_b32_e32 v2, 4, v1
	v_bitop3_b32 v2, v2, v1, 32 bitop3:0x6c
	v_ashrrev_i32_e32 v1, 31, v2
	v_lshrrev_b32_e32 v1, 26, v1
	v_add_u32_e32 v4, v2, v1
	v_lshlrev_b32_e32 v5, 3, v0
	v_ashrrev_i32_e32 v1, 6, v4
	v_and_b32_e32 v5, -16, v5
	v_add_u32_e32 v5, v1, v5
	v_and_b32_e32 v7, 3, v1
	s_mov_b32 s4, 0x1fffe0
	v_lshrrev_b32_e32 v8, 2, v5
	v_lshlrev_b32_e32 v9, 1, v5
	v_and_b32_e32 v4, 0xc0, v4
	v_and_or_b32 v7, v5, s4, v7
	v_and_b32_e32 v8, 4, v8
	v_and_b32_e32 v9, 24, v9
	v_sub_u32_e32 v2, v2, v4
	v_or3_b32 v7, v7, v8, v9
	v_lshlrev_b32_e32 v8, 5, v0
	v_ashrrev_i16_sdwa v2, v213, sext(v2) dst_sel:DWORD dst_unused:UNUSED_PAD src0_sel:DWORD src1_sel:BYTE_0
	v_and_b32_e32 v8, 32, v8
	v_bfe_i32 v2, v2, 0, 16
	v_add_lshl_u32 v4, v8, v2, 1
	v_lshl_add_u32 v128, v7, 11, v4
	v_lshl_add_u32 v130, v5, 11, v4
	v_bfe_i32 v4, v6, 27, 1
	v_lshrrev_b32_e32 v4, 22, v4
	v_add_u32_e32 v4, v3, v4
	v_and_b32_e32 v4, 0xfffffc00, v4
	v_sub_u32_e32 v3, v3, v4
	v_lshrrev_b32_e32 v4, 4, v3
	v_bitop3_b32 v5, v4, v3, 32 bitop3:0x6c
	v_ashrrev_i32_e32 v4, 31, v6
	v_lshrrev_b32_e32 v4, 26, v4
	v_ashrrev_i32_e32 v3, 31, v3
	v_add_u32_e32 v4, v6, v4
	v_lshrrev_b32_e32 v3, 26, v3
	v_ashrrev_i32_e32 v4, 6, v4
	v_add_u32_e32 v3, v5, v3
	v_lshlrev_b32_e32 v7, 3, v4
	v_ashrrev_i32_e32 v3, 6, v3
	v_and_b32_e32 v7, -16, v7
	v_add_u32_e32 v7, v3, v7
	v_and_b32_e32 v8, 3, v3
	v_lshrrev_b32_e32 v9, 2, v7
	v_lshlrev_b32_e32 v10, 1, v7
	v_and_or_b32 v8, v7, s4, v8
	v_and_b32_e32 v9, 4, v9
	v_and_b32_e32 v10, 24, v10
	v_or3_b32 v8, v8, v9, v10
	v_mul_i32_i24_e32 v10, 64, v3
	v_sub_u32_e32 v5, v5, v10
	s_ashr_i32 s1, s0, 6
	v_lshlrev_b32_e32 v9, 5, v4
	v_ashrrev_i16_sdwa v5, v213, sext(v5) dst_sel:DWORD dst_unused:UNUSED_PAD src0_sel:DWORD src1_sel:BYTE_0
	s_lshl_b32 s40, s1, 10
	v_and_b32_e32 v9, 32, v9
	v_bfe_i32 v5, v5, 0, 16
	v_add_lshl_u32 v9, v9, v5, 1
	s_add_i32 s41, s40, 0
	v_readlane_b32 s4, v252, 35
	v_lshl_add_u32 v156, v8, 11, v9
	s_add_i32 m0, s41, 0x10000
	v_readlane_b32 s5, v252, 36
	v_lshl_add_u32 v132, v7, 11, v9
	s_add_i32 s44, s41, 0x2000
	s_add_i32 s46, s41, 0x4000
	s_add_i32 s47, s41, 0x6000
	s_ashr_i32 s6, s0, 8
	global_load_lds_dwordx4 v156, s[4:5]
	s_add_i32 m0, s41, 0x12000
	s_nop 0
	global_load_lds_dwordx4 v128, s[4:5]
	v_readlane_b32 s4, v252, 33
	s_add_i32 m0, s41, 0x14000
	v_readlane_b32 s5, v252, 34
	s_nop 4
	global_load_lds_dwordx4 v156, s[4:5]
	s_add_i32 m0, s41, 0x16000
	s_cmp_eq_u32 s6, 1
	global_load_lds_dwordx4 v128, s[4:5]
	v_readlane_b32 s4, v251, 47
	s_mov_b32 m0, s41
	v_readlane_b32 s5, v251, 48
	s_nop 4
	global_load_lds_dwordx4 v132, s[4:5]
	s_mov_b32 m0, s44
	s_nop 0
	global_load_lds_dwordx4 v130, s[4:5]
	v_readlane_b32 s4, v251, 49
	s_mov_b32 m0, s46
	v_readlane_b32 s5, v251, 50
	s_nop 4
	global_load_lds_dwordx4 v132, s[4:5]
	s_mov_b32 m0, s47
	s_nop 0
	global_load_lds_dwordx4 v130, s[4:5]
	s_cselect_b64 s[4:5], -1, 0
	s_cmp_lg_u32 s6, 1
	s_cbranch_scc1 .LBB0_1090
	s_barrier

.LBB0_1096:
	s_add_u32 s18, s16, 0xfffc0080
	s_addc_u32 s19, s17, -1
	s_add_i32 s72, 0, 0x10000
	s_cmp_eq_u32 s59, 12
	s_cselect_b32 s23, s11, s19
	s_cselect_b32 s22, s53, s18
	v_add_u32_e32 v154, s72, v143
	s_cselect_b32 s19, s9, s58
	s_cselect_b32 s18, s54, s55
	s_add_i32 s86, 0, 0x14000
	ds_read_b128 v[138:141], v154
	ds_read_b128 v[146:149], v154 offset:1024
	ds_read_b128 v[150:153], v154 offset:2048
	ds_read_b128 v[172:175], v154 offset:3072
	v_add_u32_e32 v154, s86, v143
	ds_read_b128 v[180:183], v154
	ds_read_b128 v[184:187], v154 offset:1024
	ds_read_b128 v[188:191], v154 offset:2048
	ds_read_b128 v[192:195], v154 offset:3072
	v_lshl_add_u64 v[154:155], s[16:17], 0, v[134:135]
	s_add_i32 m0, s41, 0xc000
	ds_read_b128 v[196:199], v145
	ds_read_b128 v[200:203], v145 offset:1024
	ds_read_b128 v[204:207], v145 offset:2048
	ds_read_b128 v[208:211], v145 offset:3072
	ds_read_b128 v[226:229], v145 offset:4096
	ds_read_b128 v[230:233], v145 offset:5120
	ds_read_b128 v[234:237], v145 offset:6144
	ds_read_b128 v[238:241], v145 offset:7168
	global_load_lds_dwordx4 v[154:155], off
	v_lshl_add_u64 v[154:155], s[16:17], 0, v[136:137]
	s_add_i32 m0, s41, 0xe000
	s_nop 0
	global_load_lds_dwordx4 v[154:155], off
	s_waitcnt vmcnt(8)
	s_waitcnt lgkmcnt(0)
	s_barrier
	s_waitcnt lgkmcnt(0)
	v_mfma_f32_16x16x32_bf16 v[124:127], v[138:141], v[196:199], v[124:127]
	v_mfma_f32_16x16x32_bf16 v[116:119], v[150:153], v[196:199], v[116:119]
	v_mfma_f32_16x16x32_bf16 v[108:111], v[138:141], v[204:207], v[108:111]
	v_mfma_f32_16x16x32_bf16 v[100:103], v[150:153], v[204:207], v[100:103]
	v_mfma_f32_16x16x32_bf16 v[92:95], v[138:141], v[226:229], v[92:95]
	v_mfma_f32_16x16x32_bf16 v[84:87], v[150:153], v[226:229], v[84:87]
	v_mfma_f32_16x16x32_bf16 v[76:79], v[138:141], v[234:237], v[76:79]
	v_mfma_f32_16x16x32_bf16 v[68:71], v[150:153], v[234:237], v[68:71]
	v_mfma_f32_16x16x32_bf16 v[124:127], v[146:149], v[200:203], v[124:127]
	v_mfma_f32_16x16x32_bf16 v[116:119], v[172:175], v[200:203], v[116:119]
	v_mfma_f32_16x16x32_bf16 v[108:111], v[146:149], v[208:211], v[108:111]
	v_mfma_f32_16x16x32_bf16 v[100:103], v[172:175], v[208:211], v[100:103]
	v_mfma_f32_16x16x32_bf16 v[92:95], v[146:149], v[230:233], v[92:95]
	v_mfma_f32_16x16x32_bf16 v[84:87], v[172:175], v[230:233], v[84:87]
	v_mfma_f32_16x16x32_bf16 v[76:79], v[146:149], v[238:241], v[76:79]
	v_mfma_f32_16x16x32_bf16 v[68:71], v[172:175], v[238:241], v[68:71]
	v_mfma_f32_16x16x32_bf16 v[120:123], v[180:183], v[196:199], v[120:123]
	v_mfma_f32_16x16x32_bf16 v[112:115], v[188:191], v[196:199], v[112:115]
	v_mfma_f32_16x16x32_bf16 v[104:107], v[180:183], v[204:207], v[104:107]
	v_mfma_f32_16x16x32_bf16 v[96:99], v[188:191], v[204:207], v[96:99]
	v_mfma_f32_16x16x32_bf16 v[88:91], v[180:183], v[226:229], v[88:91]
	v_mfma_f32_16x16x32_bf16 v[80:83], v[188:191], v[226:229], v[80:83]
	v_mfma_f32_16x16x32_bf16 v[72:75], v[180:183], v[234:237], v[72:75]
	v_mfma_f32_16x16x32_bf16 v[64:67], v[188:191], v[234:237], v[64:67]
	v_mfma_f32_16x16x32_bf16 v[120:123], v[184:187], v[200:203], v[120:123]
	v_mfma_f32_16x16x32_bf16 v[112:115], v[192:195], v[200:203], v[112:115]
	v_mfma_f32_16x16x32_bf16 v[104:107], v[184:187], v[208:211], v[104:107]
	v_mfma_f32_16x16x32_bf16 v[96:99], v[192:195], v[208:211], v[96:99]
	v_mfma_f32_16x16x32_bf16 v[88:91], v[184:187], v[230:233], v[88:91]
	v_mfma_f32_16x16x32_bf16 v[80:83], v[192:195], v[230:233], v[80:83]
	v_mfma_f32_16x16x32_bf16 v[72:75], v[184:187], v[238:241], v[72:75]
	v_mfma_f32_16x16x32_bf16 v[64:67], v[192:195], v[238:241], v[64:67]
	s_barrier
	s_add_i32 s72, s72, s40
	v_lshl_add_u64 v[154:155], s[18:19], 0, v[156:157]
	s_mov_b32 m0, s72
	ds_read_b128 v[196:199], v145 offset:16384
	ds_read_b128 v[200:203], v145 offset:17408
	ds_read_b128 v[204:207], v145 offset:18432
	ds_read_b128 v[208:211], v145 offset:19456
	ds_read_b128 v[226:229], v145 offset:20480
	ds_read_b128 v[230:233], v145 offset:21504
	ds_read_b128 v[234:237], v145 offset:22528
	ds_read_b128 v[238:241], v145 offset:23552
	global_load_lds_dwordx4 v[154:155], off
	s_add_i32 m0, s72, 0x2000
	s_add_u32 s72, s18, 0x40000
	v_lshl_add_u64 v[176:177], s[18:19], 0, v[128:129]
	s_addc_u32 s73, s19, 0
	s_add_i32 s86, s86, s40
	global_load_lds_dwordx4 v[176:177], off
	v_lshl_add_u64 v[242:243], s[72:73], 0, v[156:157]
	s_mov_b32 m0, s86
	v_lshl_add_u64 v[244:245], s[22:23], 0, v[130:131]
	global_load_lds_dwordx4 v[242:243], off
	v_lshl_add_u64 v[242:243], s[72:73], 0, v[128:129]
	s_add_i32 m0, s86, 0x2000
	s_nop 0
	global_load_lds_dwordx4 v[242:243], off
	v_lshl_add_u64 v[242:243], s[22:23], 0, v[132:133]
	s_mov_b32 m0, s41
	s_nop 0
	global_load_lds_dwordx4 v[242:243], off
	s_mov_b32 m0, s44
	s_nop 0
	global_load_lds_dwordx4 v[244:245], off
	s_waitcnt vmcnt(8)
	s_waitcnt lgkmcnt(0)
	s_barrier
	s_waitcnt lgkmcnt(0)
	v_mfma_f32_16x16x32_bf16 v[60:63], v[138:141], v[196:199], v[60:63]
	v_mfma_f32_16x16x32_bf16 v[52:55], v[150:153], v[196:199], v[52:55]
	v_mfma_f32_16x16x32_bf16 v[44:47], v[138:141], v[204:207], v[44:47]
	v_mfma_f32_16x16x32_bf16 v[36:39], v[150:153], v[204:207], v[36:39]
	v_mfma_f32_16x16x32_bf16 v[28:31], v[138:141], v[226:229], v[28:31]
	v_mfma_f32_16x16x32_bf16 v[20:23], v[150:153], v[226:229], v[20:23]
	v_mfma_f32_16x16x32_bf16 v[12:15], v[138:141], v[234:237], v[12:15]
	v_mfma_f32_16x16x32_bf16 v[4:7], v[150:153], v[234:237], v[4:7]
	v_mfma_f32_16x16x32_bf16 v[60:63], v[146:149], v[200:203], v[60:63]
	v_mfma_f32_16x16x32_bf16 v[52:55], v[172:175], v[200:203], v[52:55]
	v_mfma_f32_16x16x32_bf16 v[44:47], v[146:149], v[208:211], v[44:47]
	v_mfma_f32_16x16x32_bf16 v[36:39], v[172:175], v[208:211], v[36:39]
	v_mfma_f32_16x16x32_bf16 v[28:31], v[146:149], v[230:233], v[28:31]
	v_mfma_f32_16x16x32_bf16 v[20:23], v[172:175], v[230:233], v[20:23]
	v_mfma_f32_16x16x32_bf16 v[12:15], v[146:149], v[238:241], v[12:15]
	v_mfma_f32_16x16x32_bf16 v[4:7], v[172:175], v[238:241], v[4:7]
	v_mfma_f32_16x16x32_bf16 v[56:59], v[180:183], v[196:199], v[56:59]
	v_mfma_f32_16x16x32_bf16 v[48:51], v[188:191], v[196:199], v[48:51]
	v_mfma_f32_16x16x32_bf16 v[40:43], v[180:183], v[204:207], v[40:43]
	v_mfma_f32_16x16x32_bf16 v[32:35], v[188:191], v[204:207], v[32:35]
	v_mfma_f32_16x16x32_bf16 v[24:27], v[180:183], v[226:229], v[24:27]
	v_mfma_f32_16x16x32_bf16 v[16:19], v[188:191], v[226:229], v[16:19]
	v_mfma_f32_16x16x32_bf16 v[8:11], v[180:183], v[234:237], v[8:11]
	v_mfma_f32_16x16x32_bf16 v[0:3], v[188:191], v[234:237], v[0:3]
	v_mfma_f32_16x16x32_bf16 v[56:59], v[184:187], v[200:203], v[56:59]
	v_mfma_f32_16x16x32_bf16 v[48:51], v[192:195], v[200:203], v[48:51]
	v_mfma_f32_16x16x32_bf16 v[40:43], v[184:187], v[208:211], v[40:43]
	v_mfma_f32_16x16x32_bf16 v[32:35], v[192:195], v[208:211], v[32:35]
	v_mfma_f32_16x16x32_bf16 v[24:27], v[184:187], v[230:233], v[24:27]
	v_mfma_f32_16x16x32_bf16 v[16:19], v[192:195], v[230:233], v[16:19]
	v_mfma_f32_16x16x32_bf16 v[8:11], v[184:187], v[238:241], v[8:11]
	v_mfma_f32_16x16x32_bf16 v[0:3], v[192:195], v[238:241], v[0:3]
	s_barrier
	s_add_i32 s72, 0, 0x18000
	s_add_i32 s73, 0, 0x1c000
	v_add_u32_e32 v172, s72, v143
	v_add_u32_e32 v178, s73, v143
	ds_read_b128 v[138:141], v172
	ds_read_b128 v[146:149], v172 offset:1024
	ds_read_b128 v[150:153], v172 offset:2048
	ds_read_b128 v[172:175], v172 offset:3072
	ds_read_b128 v[180:183], v178
	ds_read_b128 v[184:187], v178 offset:1024
	ds_read_b128 v[188:191], v178 offset:2048
	ds_read_b128 v[192:195], v178 offset:3072
	s_add_u32 s22, s22, 0x40000
	s_addc_u32 s23, s23, 0
	s_mov_b32 m0, s46
	v_lshl_add_u64 v[246:247], s[22:23], 0, v[132:133]
	ds_read_b128 v[196:199], v145 offset:32768
	ds_read_b128 v[200:203], v145 offset:33792
	ds_read_b128 v[204:207], v145 offset:34816
	ds_read_b128 v[208:211], v145 offset:35840
	ds_read_b128 v[226:229], v145 offset:36864
	ds_read_b128 v[230:233], v145 offset:37888
	ds_read_b128 v[234:237], v145 offset:38912
	ds_read_b128 v[238:241], v145 offset:39936
	global_load_lds_dwordx4 v[246:247], off
	v_lshl_add_u64 v[246:247], s[22:23], 0, v[130:131]
	s_mov_b32 m0, s47
	s_nop 0
	global_load_lds_dwordx4 v[246:247], off
	s_waitcnt vmcnt(8)
	s_waitcnt lgkmcnt(0)
	s_barrier
	s_waitcnt lgkmcnt(0)
	v_mfma_f32_16x16x32_bf16 v[124:127], v[138:141], v[196:199], v[124:127]
	v_mfma_f32_16x16x32_bf16 v[116:119], v[150:153], v[196:199], v[116:119]
	v_mfma_f32_16x16x32_bf16 v[108:111], v[138:141], v[204:207], v[108:111]
	v_mfma_f32_16x16x32_bf16 v[100:103], v[150:153], v[204:207], v[100:103]
	v_mfma_f32_16x16x32_bf16 v[92:95], v[138:141], v[226:229], v[92:95]
	v_mfma_f32_16x16x32_bf16 v[84:87], v[150:153], v[226:229], v[84:87]
	v_mfma_f32_16x16x32_bf16 v[76:79], v[138:141], v[234:237], v[76:79]
	v_mfma_f32_16x16x32_bf16 v[68:71], v[150:153], v[234:237], v[68:71]
	v_mfma_f32_16x16x32_bf16 v[124:127], v[146:149], v[200:203], v[124:127]
	v_mfma_f32_16x16x32_bf16 v[116:119], v[172:175], v[200:203], v[116:119]
	v_mfma_f32_16x16x32_bf16 v[108:111], v[146:149], v[208:211], v[108:111]
	v_mfma_f32_16x16x32_bf16 v[100:103], v[172:175], v[208:211], v[100:103]
	v_mfma_f32_16x16x32_bf16 v[92:95], v[146:149], v[230:233], v[92:95]
	v_mfma_f32_16x16x32_bf16 v[84:87], v[172:175], v[230:233], v[84:87]
	v_mfma_f32_16x16x32_bf16 v[76:79], v[146:149], v[238:241], v[76:79]
	v_mfma_f32_16x16x32_bf16 v[68:71], v[172:175], v[238:241], v[68:71]
	v_mfma_f32_16x16x32_bf16 v[120:123], v[180:183], v[196:199], v[120:123]
	v_mfma_f32_16x16x32_bf16 v[112:115], v[188:191], v[196:199], v[112:115]
	v_mfma_f32_16x16x32_bf16 v[104:107], v[180:183], v[204:207], v[104:107]
	v_mfma_f32_16x16x32_bf16 v[96:99], v[188:191], v[204:207], v[96:99]
	v_mfma_f32_16x16x32_bf16 v[88:91], v[180:183], v[226:229], v[88:91]
	v_mfma_f32_16x16x32_bf16 v[80:83], v[188:191], v[226:229], v[80:83]
	v_mfma_f32_16x16x32_bf16 v[72:75], v[180:183], v[234:237], v[72:75]
	v_mfma_f32_16x16x32_bf16 v[64:67], v[188:191], v[234:237], v[64:67]
	v_mfma_f32_16x16x32_bf16 v[120:123], v[184:187], v[200:203], v[120:123]
	v_mfma_f32_16x16x32_bf16 v[112:115], v[192:195], v[200:203], v[112:115]
	v_mfma_f32_16x16x32_bf16 v[104:107], v[184:187], v[208:211], v[104:107]
	v_mfma_f32_16x16x32_bf16 v[96:99], v[192:195], v[208:211], v[96:99]
	v_mfma_f32_16x16x32_bf16 v[88:91], v[184:187], v[230:233], v[88:91]
	v_mfma_f32_16x16x32_bf16 v[80:83], v[192:195], v[230:233], v[80:83]
	v_mfma_f32_16x16x32_bf16 v[72:75], v[184:187], v[238:241], v[72:75]
	v_mfma_f32_16x16x32_bf16 v[64:67], v[192:195], v[238:241], v[64:67]
	s_barrier
	s_add_i32 s22, s72, s40
	v_lshl_add_u64 v[154:155], v[154:155], 0, s[64:65]
	s_mov_b32 m0, s22
	ds_read_b128 v[196:199], v145 offset:49152
	ds_read_b128 v[200:203], v145 offset:50176
	ds_read_b128 v[204:207], v145 offset:51200
	ds_read_b128 v[208:211], v145 offset:52224
	ds_read_b128 v[226:229], v145 offset:53248
	ds_read_b128 v[230:233], v145 offset:54272
	ds_read_b128 v[234:237], v145 offset:55296
	ds_read_b128 v[238:241], v145 offset:56320
	global_load_lds_dwordx4 v[154:155], off
	s_add_i32 m0, s22, 0x2000
	s_add_u32 s18, s18, 0x40080
	v_lshl_add_u64 v[154:155], v[176:177], 0, s[64:65]
	s_addc_u32 s19, s19, 0
	s_add_i32 s22, s73, s40
	global_load_lds_dwordx4 v[154:155], off
	v_lshl_add_u64 v[154:155], s[18:19], 0, v[156:157]
	s_mov_b32 m0, s22
	s_nop 0
	global_load_lds_dwordx4 v[154:155], off
	v_lshl_add_u64 v[154:155], s[18:19], 0, v[128:129]
	s_add_i32 m0, s22, 0x2000
	s_nop 0
	global_load_lds_dwordx4 v[154:155], off
	v_lshl_add_u64 v[154:155], v[242:243], 0, s[64:65]
	s_mov_b32 m0, s48
	s_nop 0
	global_load_lds_dwordx4 v[154:155], off
	v_lshl_add_u64 v[154:155], v[244:245], 0, s[64:65]
	s_mov_b32 m0, s49
	s_nop 0
	global_load_lds_dwordx4 v[154:155], off
	s_waitcnt vmcnt(8)
	s_waitcnt lgkmcnt(0)
	s_barrier
	s_waitcnt lgkmcnt(0)
	v_mfma_f32_16x16x32_bf16 v[60:63], v[138:141], v[196:199], v[60:63]
	v_mfma_f32_16x16x32_bf16 v[52:55], v[150:153], v[196:199], v[52:55]
	v_mfma_f32_16x16x32_bf16 v[44:47], v[138:141], v[204:207], v[44:47]
	v_mfma_f32_16x16x32_bf16 v[36:39], v[150:153], v[204:207], v[36:39]
	v_mfma_f32_16x16x32_bf16 v[28:31], v[138:141], v[226:229], v[28:31]
	v_mfma_f32_16x16x32_bf16 v[20:23], v[150:153], v[226:229], v[20:23]
	v_mfma_f32_16x16x32_bf16 v[12:15], v[138:141], v[234:237], v[12:15]
	v_mfma_f32_16x16x32_bf16 v[4:7], v[150:153], v[234:237], v[4:7]
	v_mfma_f32_16x16x32_bf16 v[60:63], v[146:149], v[200:203], v[60:63]
	v_mfma_f32_16x16x32_bf16 v[52:55], v[172:175], v[200:203], v[52:55]
	v_mfma_f32_16x16x32_bf16 v[44:47], v[146:149], v[208:211], v[44:47]
	v_mfma_f32_16x16x32_bf16 v[36:39], v[172:175], v[208:211], v[36:39]
	v_mfma_f32_16x16x32_bf16 v[28:31], v[146:149], v[230:233], v[28:31]
	v_mfma_f32_16x16x32_bf16 v[20:23], v[172:175], v[230:233], v[20:23]
	v_mfma_f32_16x16x32_bf16 v[12:15], v[146:149], v[238:241], v[12:15]
	v_mfma_f32_16x16x32_bf16 v[4:7], v[172:175], v[238:241], v[4:7]
	v_mfma_f32_16x16x32_bf16 v[56:59], v[180:183], v[196:199], v[56:59]
	v_mfma_f32_16x16x32_bf16 v[48:51], v[188:191], v[196:199], v[48:51]
	v_mfma_f32_16x16x32_bf16 v[40:43], v[180:183], v[204:207], v[40:43]
	v_mfma_f32_16x16x32_bf16 v[32:35], v[188:191], v[204:207], v[32:35]
	v_mfma_f32_16x16x32_bf16 v[24:27], v[180:183], v[226:229], v[24:27]
	v_mfma_f32_16x16x32_bf16 v[16:19], v[188:191], v[226:229], v[16:19]
	v_mfma_f32_16x16x32_bf16 v[8:11], v[180:183], v[234:237], v[8:11]
	v_mfma_f32_16x16x32_bf16 v[0:3], v[188:191], v[234:237], v[0:3]
	v_mfma_f32_16x16x32_bf16 v[56:59], v[184:187], v[200:203], v[56:59]
	v_mfma_f32_16x16x32_bf16 v[48:51], v[192:195], v[200:203], v[48:51]
	v_mfma_f32_16x16x32_bf16 v[40:43], v[184:187], v[208:211], v[40:43]
	v_mfma_f32_16x16x32_bf16 v[32:35], v[192:195], v[208:211], v[32:35]
	v_mfma_f32_16x16x32_bf16 v[24:27], v[184:187], v[230:233], v[24:27]
	v_mfma_f32_16x16x32_bf16 v[16:19], v[192:195], v[230:233], v[16:19]
	v_mfma_f32_16x16x32_bf16 v[8:11], v[184:187], v[238:241], v[8:11]
	v_mfma_f32_16x16x32_bf16 v[0:3], v[192:195], v[238:241], v[0:3]
	s_barrier
	s_add_i32 s59, s59, 2
	s_add_u32 s16, s16, 0x100
	s_addc_u32 s17, s17, 0
	s_add_u32 s55, s55, 0x100
	s_addc_u32 s58, s58, 0
	s_cmp_gt_u32 s59, 13
	s_cbranch_scc0 .LBB0_1096
	s_and_b64 vcc, exec, s[6:7]
	s_cbranch_vccz .LBB0_1099
	s_barrier

.Lprio_done5:
	v_lshlrev_b32_e32 v4, 4, v8
	v_add_u32_e32 v1, 0x2000, v4
	v_ashrrev_i32_e32 v0, 31, v1
	v_lshrrev_b32_e32 v0, 22, v0
	v_add_u32_e32 v0, v1, v0
	v_ashrrev_i32_e32 v0, 10, v0
	v_mul_i32_i24_e32 v2, 0x400, v0
	v_sub_u32_e32 v1, v1, v2
	v_lshrrev_b32_e32 v2, 4, v1
	v_bitop3_b32 v3, v2, v1, 32 bitop3:0x6c
	v_ashrrev_i32_e32 v1, 31, v3
	v_lshrrev_b32_e32 v1, 26, v1
	v_add_u32_e32 v5, v3, v1
	v_ashrrev_i32_e32 v1, 6, v5
	v_and_b32_e32 v5, 0xc0, v5
	v_sub_u32_e32 v3, v3, v5
	v_bfe_i32 v5, v8, 27, 1
	v_lshrrev_b32_e32 v5, 22, v5
	v_add_u32_e32 v5, v4, v5
	v_and_b32_e32 v5, 0xfffffc00, v5
	v_lshlrev_b32_e32 v2, 3, v0
	v_sub_u32_e32 v4, v4, v5
	v_and_b32_e32 v2, 0xfffff0, v2
	v_lshrrev_b32_e32 v5, 4, v4
	v_add_u32_e32 v2, v1, v2
	s_movk_i32 s4, 0xb00
	v_bitop3_b32 v7, v5, v4, 32 bitop3:0x6c
	v_ashrrev_i32_e32 v5, 31, v8
	v_mul_lo_u32 v6, v2, s4
	v_lshlrev_b32_e32 v2, 5, v0
	v_lshrrev_b32_e32 v5, 26, v5
	v_and_b32_e32 v2, 32, v2
	v_ashrrev_i16_sdwa v3, v213, sext(v3) dst_sel:DWORD dst_unused:UNUSED_PAD src0_sel:DWORD src1_sel:BYTE_0
	v_ashrrev_i32_e32 v4, 31, v4
	v_add_u32_e32 v5, v8, v5
	v_or_b32_e32 v6, v6, v2
	v_bfe_i32 v3, v3, 0, 16
	v_lshrrev_b32_e32 v4, 26, v4
	v_ashrrev_i32_e32 v5, 6, v5
	v_add_lshl_u32 v128, v6, v3, 1
	v_add_u32_e32 v4, v7, v4
	v_lshlrev_b32_e32 v6, 3, v5
	v_ashrrev_i32_e32 v4, 6, v4
	v_and_b32_e32 v6, 0xfffff0, v6
	v_add_u32_e32 v6, v4, v6
	v_mul_i32_i24_e32 v10, 64, v4
	s_ashr_i32 s1, s0, 6
	v_mul_lo_u32 v9, v6, s4
	v_lshlrev_b32_e32 v6, 5, v5
	v_sub_u32_e32 v7, v7, v10
	s_lshl_b32 s22, s1, 10
	v_and_b32_e32 v6, 32, v6
	v_ashrrev_i16_sdwa v7, v213, sext(v7) dst_sel:DWORD dst_unused:UNUSED_PAD src0_sel:DWORD src1_sel:BYTE_0
	v_or_b32_e32 v9, v9, v6
	v_bfe_i32 v7, v7, 0, 16
	s_add_i32 s23, s22, 0
	v_readlane_b32 s4, v252, 43
	v_add_lshl_u32 v156, v9, v7, 1
	s_add_i32 m0, s23, 0x10000
	v_readlane_b32 s5, v252, 44
	s_add_i32 s40, s23, 0x2000
	s_add_i32 s41, s23, 0x4000
	s_add_i32 s44, s23, 0x6000
	s_mov_b32 s10, 0xb000
	s_nop 0
	global_load_lds_dwordx4 v156, s[4:5]
	s_add_i32 m0, s23, 0x12000
	s_nop 0
	global_load_lds_dwordx4 v128, s[4:5]
	v_readlane_b32 s4, v252, 41
	s_add_i32 m0, s23, 0x14000
	v_readlane_b32 s5, v252, 42
	s_nop 4
	global_load_lds_dwordx4 v156, s[4:5]
	s_add_i32 m0, s23, 0x16000
	s_nop 0
	global_load_lds_dwordx4 v128, s[4:5]
	v_readlane_b32 s4, v251, 60
	s_mov_b32 m0, s23
	v_readlane_b32 s5, v251, 61
	s_nop 4
	global_load_lds_dwordx4 v156, s[4:5]
	s_mov_b32 m0, s40
	s_nop 0
	global_load_lds_dwordx4 v128, s[4:5]
	v_readlane_b32 s4, v251, 62
	s_mov_b32 m0, s41
	v_readlane_b32 s5, v251, 63
	s_nop 4
	global_load_lds_dwordx4 v156, s[4:5]
	s_mov_b32 m0, s44
	s_nop 0
	global_load_lds_dwordx4 v128, s[4:5]
	s_ashr_i32 s4, s0, 8
	s_cmp_eq_u32 s4, 1
	s_cselect_b64 s[6:7], -1, 0
	s_cmp_lg_u32 s4, 1
	s_cbranch_scc1 .LBB0_1158
	s_barrier

.LBB0_1172:
	s_add_u32 s14, s12, 0x100
	s_addc_u32 s15, s13, 0
	s_add_i32 s72, 0, 0x10000
	s_cmp_eq_u32 s59, 40
	s_cselect_b32 s19, s5, s15
	s_cselect_b32 s18, s4, s14
	s_cselect_b32 s17, s11, s58
	s_cselect_b32 s16, s10, s55
	s_add_i32 s73, 0, 0x14000
	v_add_u32_e32 v146, s72, v155
	v_add_u32_e32 v178, s73, v155
	ds_read_b128 v[134:137], v146
	ds_read_b128 v[138:141], v146 offset:1024
	ds_read_b128 v[142:145], v146 offset:2048
	ds_read_b128 v[146:149], v146 offset:3072
	ds_read_b128 v[150:153], v178
	ds_read_b128 v[174:177], v178 offset:1024
	ds_read_b128 v[180:183], v178 offset:2048
	ds_read_b128 v[184:187], v178 offset:3072
	v_lshl_add_u64 v[234:235], s[12:13], 0, v[130:131]
	s_add_i32 m0, s23, 0xc000
	ds_read_b128 v[188:191], v173
	ds_read_b128 v[192:195], v173 offset:1024
	ds_read_b128 v[196:199], v173 offset:2048
	ds_read_b128 v[200:203], v173 offset:3072
	ds_read_b128 v[204:207], v173 offset:4096
	ds_read_b128 v[208:211], v173 offset:5120
	ds_read_b128 v[226:229], v173 offset:6144
	ds_read_b128 v[230:233], v173 offset:7168
	global_load_lds_dwordx4 v[234:235], off
	v_lshl_add_u64 v[234:235], s[12:13], 0, v[132:133]
	s_add_i32 m0, s23, 0xe000
	s_nop 0
	global_load_lds_dwordx4 v[234:235], off
	s_waitcnt vmcnt(8)
	s_waitcnt lgkmcnt(0)
	s_barrier
	s_waitcnt lgkmcnt(0)
	v_mfma_f32_16x16x32_bf16 v[124:127], v[134:137], v[188:191], v[124:127]
	v_mfma_f32_16x16x32_bf16 v[120:123], v[142:145], v[188:191], v[120:123]
	v_mfma_f32_16x16x32_bf16 v[108:111], v[134:137], v[196:199], v[108:111]
	v_mfma_f32_16x16x32_bf16 v[104:107], v[142:145], v[196:199], v[104:107]
	v_mfma_f32_16x16x32_bf16 v[92:95], v[134:137], v[204:207], v[92:95]
	v_mfma_f32_16x16x32_bf16 v[88:91], v[142:145], v[204:207], v[88:91]
	v_mfma_f32_16x16x32_bf16 v[76:79], v[134:137], v[226:229], v[76:79]
	v_mfma_f32_16x16x32_bf16 v[72:75], v[142:145], v[226:229], v[72:75]
	v_mfma_f32_16x16x32_bf16 v[124:127], v[138:141], v[192:195], v[124:127]
	v_mfma_f32_16x16x32_bf16 v[120:123], v[146:149], v[192:195], v[120:123]
	v_mfma_f32_16x16x32_bf16 v[108:111], v[138:141], v[200:203], v[108:111]
	v_mfma_f32_16x16x32_bf16 v[104:107], v[146:149], v[200:203], v[104:107]
	v_mfma_f32_16x16x32_bf16 v[92:95], v[138:141], v[208:211], v[92:95]
	v_mfma_f32_16x16x32_bf16 v[88:91], v[146:149], v[208:211], v[88:91]
	v_mfma_f32_16x16x32_bf16 v[76:79], v[138:141], v[230:233], v[76:79]
	v_mfma_f32_16x16x32_bf16 v[72:75], v[146:149], v[230:233], v[72:75]
	v_mfma_f32_16x16x32_bf16 v[116:119], v[150:153], v[188:191], v[116:119]
	v_mfma_f32_16x16x32_bf16 v[112:115], v[180:183], v[188:191], v[112:115]
	v_mfma_f32_16x16x32_bf16 v[100:103], v[150:153], v[196:199], v[100:103]
	v_mfma_f32_16x16x32_bf16 v[96:99], v[180:183], v[196:199], v[96:99]
	v_mfma_f32_16x16x32_bf16 v[84:87], v[150:153], v[204:207], v[84:87]
	v_mfma_f32_16x16x32_bf16 v[80:83], v[180:183], v[204:207], v[80:83]
	v_mfma_f32_16x16x32_bf16 v[68:71], v[150:153], v[226:229], v[68:71]
	v_mfma_f32_16x16x32_bf16 v[64:67], v[180:183], v[226:229], v[64:67]
	v_mfma_f32_16x16x32_bf16 v[116:119], v[174:177], v[192:195], v[116:119]
	v_mfma_f32_16x16x32_bf16 v[112:115], v[184:187], v[192:195], v[112:115]
	v_mfma_f32_16x16x32_bf16 v[100:103], v[174:177], v[200:203], v[100:103]
	v_mfma_f32_16x16x32_bf16 v[96:99], v[184:187], v[200:203], v[96:99]
	v_mfma_f32_16x16x32_bf16 v[84:87], v[174:177], v[208:211], v[84:87]
	v_mfma_f32_16x16x32_bf16 v[80:83], v[184:187], v[208:211], v[80:83]
	v_mfma_f32_16x16x32_bf16 v[68:71], v[174:177], v[230:233], v[68:71]
	v_mfma_f32_16x16x32_bf16 v[64:67], v[184:187], v[230:233], v[64:67]
	s_barrier
	s_add_i32 s12, s72, s22
	v_lshl_add_u64 v[234:235], s[16:17], 0, v[156:157]
	s_mov_b32 m0, s12
	ds_read_b128 v[188:191], v173 offset:16384
	ds_read_b128 v[192:195], v173 offset:17408
	ds_read_b128 v[196:199], v173 offset:18432
	ds_read_b128 v[200:203], v173 offset:19456
	ds_read_b128 v[204:207], v173 offset:20480
	ds_read_b128 v[208:211], v173 offset:21504
	ds_read_b128 v[226:229], v173 offset:22528
	ds_read_b128 v[230:233], v173 offset:23552
	global_load_lds_dwordx4 v[234:235], off
	s_add_i32 m0, s12, 0x2000
	s_add_u32 s12, s16, 0xb0000
	v_lshl_add_u64 v[236:237], s[16:17], 0, v[128:129]
	s_addc_u32 s13, s17, 0
	s_add_i32 s72, s73, s22
	global_load_lds_dwordx4 v[236:237], off
	v_lshl_add_u64 v[238:239], s[12:13], 0, v[156:157]
	s_mov_b32 m0, s72
	v_lshl_add_u64 v[240:241], s[18:19], 0, v[128:129]
	global_load_lds_dwordx4 v[238:239], off
	v_lshl_add_u64 v[238:239], s[12:13], 0, v[128:129]
	s_add_i32 m0, s72, 0x2000
	s_nop 0
	global_load_lds_dwordx4 v[238:239], off
	v_lshl_add_u64 v[238:239], s[18:19], 0, v[156:157]
	s_mov_b32 m0, s23
	s_nop 0
	global_load_lds_dwordx4 v[238:239], off
	s_mov_b32 m0, s40
	s_nop 0
	global_load_lds_dwordx4 v[240:241], off
	s_waitcnt vmcnt(8)
	s_waitcnt lgkmcnt(0)
	s_barrier
	s_waitcnt lgkmcnt(0)
	v_mfma_f32_16x16x32_bf16 v[60:63], v[134:137], v[188:191], v[60:63]
	v_mfma_f32_16x16x32_bf16 v[56:59], v[142:145], v[188:191], v[56:59]
	v_mfma_f32_16x16x32_bf16 v[44:47], v[134:137], v[196:199], v[44:47]
	v_mfma_f32_16x16x32_bf16 v[40:43], v[142:145], v[196:199], v[40:43]
	v_mfma_f32_16x16x32_bf16 v[28:31], v[134:137], v[204:207], v[28:31]
	v_mfma_f32_16x16x32_bf16 v[24:27], v[142:145], v[204:207], v[24:27]
	v_mfma_f32_16x16x32_bf16 v[12:15], v[134:137], v[226:229], v[12:15]
	v_mfma_f32_16x16x32_bf16 v[8:11], v[142:145], v[226:229], v[8:11]
	v_mfma_f32_16x16x32_bf16 v[60:63], v[138:141], v[192:195], v[60:63]
	v_mfma_f32_16x16x32_bf16 v[56:59], v[146:149], v[192:195], v[56:59]
	v_mfma_f32_16x16x32_bf16 v[44:47], v[138:141], v[200:203], v[44:47]
	v_mfma_f32_16x16x32_bf16 v[40:43], v[146:149], v[200:203], v[40:43]
	v_mfma_f32_16x16x32_bf16 v[28:31], v[138:141], v[208:211], v[28:31]
	v_mfma_f32_16x16x32_bf16 v[24:27], v[146:149], v[208:211], v[24:27]
	v_mfma_f32_16x16x32_bf16 v[12:15], v[138:141], v[230:233], v[12:15]
	v_mfma_f32_16x16x32_bf16 v[8:11], v[146:149], v[230:233], v[8:11]
	v_mfma_f32_16x16x32_bf16 v[52:55], v[150:153], v[188:191], v[52:55]
	v_mfma_f32_16x16x32_bf16 v[48:51], v[180:183], v[188:191], v[48:51]
	v_mfma_f32_16x16x32_bf16 v[36:39], v[150:153], v[196:199], v[36:39]
	v_mfma_f32_16x16x32_bf16 v[32:35], v[180:183], v[196:199], v[32:35]
	v_mfma_f32_16x16x32_bf16 v[20:23], v[150:153], v[204:207], v[20:23]
	v_mfma_f32_16x16x32_bf16 v[16:19], v[180:183], v[204:207], v[16:19]
	v_mfma_f32_16x16x32_bf16 v[4:7], v[150:153], v[226:229], v[4:7]
	v_mfma_f32_16x16x32_bf16 v[0:3], v[180:183], v[226:229], v[0:3]
	v_mfma_f32_16x16x32_bf16 v[52:55], v[174:177], v[192:195], v[52:55]
	v_mfma_f32_16x16x32_bf16 v[48:51], v[184:187], v[192:195], v[48:51]
	v_mfma_f32_16x16x32_bf16 v[36:39], v[174:177], v[200:203], v[36:39]
	v_mfma_f32_16x16x32_bf16 v[32:35], v[184:187], v[200:203], v[32:35]
	v_mfma_f32_16x16x32_bf16 v[20:23], v[174:177], v[208:211], v[20:23]
	v_mfma_f32_16x16x32_bf16 v[16:19], v[184:187], v[208:211], v[16:19]
	v_mfma_f32_16x16x32_bf16 v[4:7], v[174:177], v[230:233], v[4:7]
	v_mfma_f32_16x16x32_bf16 v[0:3], v[184:187], v[230:233], v[0:3]
	s_barrier
	s_add_i32 s72, 0, 0x18000
	s_add_i32 s73, 0, 0x1c000
	v_add_u32_e32 v146, s72, v155
	v_add_u32_e32 v178, s73, v155
	ds_read_b128 v[134:137], v146
	ds_read_b128 v[138:141], v146 offset:1024
	ds_read_b128 v[142:145], v146 offset:2048
	ds_read_b128 v[146:149], v146 offset:3072
	ds_read_b128 v[150:153], v178
	ds_read_b128 v[174:177], v178 offset:1024
	ds_read_b128 v[180:183], v178 offset:2048
	ds_read_b128 v[184:187], v178 offset:3072
	s_add_u32 s12, s18, 0xb0000
	s_addc_u32 s13, s19, 0
	s_mov_b32 m0, s41
	v_lshl_add_u64 v[242:243], s[12:13], 0, v[156:157]
	ds_read_b128 v[188:191], v173 offset:32768
	ds_read_b128 v[192:195], v173 offset:33792
	ds_read_b128 v[196:199], v173 offset:34816
	ds_read_b128 v[200:203], v173 offset:35840
	ds_read_b128 v[204:207], v173 offset:36864
	ds_read_b128 v[208:211], v173 offset:37888
	ds_read_b128 v[226:229], v173 offset:38912
	ds_read_b128 v[230:233], v173 offset:39936
	global_load_lds_dwordx4 v[242:243], off
	v_lshl_add_u64 v[242:243], s[12:13], 0, v[128:129]
	s_mov_b32 m0, s44
	s_nop 0
	global_load_lds_dwordx4 v[242:243], off
	s_waitcnt vmcnt(8)
	s_waitcnt lgkmcnt(0)
	s_barrier
	s_waitcnt lgkmcnt(0)
	v_mfma_f32_16x16x32_bf16 v[124:127], v[134:137], v[188:191], v[124:127]
	v_mfma_f32_16x16x32_bf16 v[120:123], v[142:145], v[188:191], v[120:123]
	v_mfma_f32_16x16x32_bf16 v[108:111], v[134:137], v[196:199], v[108:111]
	v_mfma_f32_16x16x32_bf16 v[104:107], v[142:145], v[196:199], v[104:107]
	v_mfma_f32_16x16x32_bf16 v[92:95], v[134:137], v[204:207], v[92:95]
	v_mfma_f32_16x16x32_bf16 v[88:91], v[142:145], v[204:207], v[88:91]
	v_mfma_f32_16x16x32_bf16 v[76:79], v[134:137], v[226:229], v[76:79]
	v_mfma_f32_16x16x32_bf16 v[72:75], v[142:145], v[226:229], v[72:75]
	v_mfma_f32_16x16x32_bf16 v[124:127], v[138:141], v[192:195], v[124:127]
	v_mfma_f32_16x16x32_bf16 v[120:123], v[146:149], v[192:195], v[120:123]
	v_mfma_f32_16x16x32_bf16 v[108:111], v[138:141], v[200:203], v[108:111]
	v_mfma_f32_16x16x32_bf16 v[104:107], v[146:149], v[200:203], v[104:107]
	v_mfma_f32_16x16x32_bf16 v[92:95], v[138:141], v[208:211], v[92:95]
	v_mfma_f32_16x16x32_bf16 v[88:91], v[146:149], v[208:211], v[88:91]
	v_mfma_f32_16x16x32_bf16 v[76:79], v[138:141], v[230:233], v[76:79]
	v_mfma_f32_16x16x32_bf16 v[72:75], v[146:149], v[230:233], v[72:75]
	v_mfma_f32_16x16x32_bf16 v[116:119], v[150:153], v[188:191], v[116:119]
	v_mfma_f32_16x16x32_bf16 v[112:115], v[180:183], v[188:191], v[112:115]
	v_mfma_f32_16x16x32_bf16 v[100:103], v[150:153], v[196:199], v[100:103]
	v_mfma_f32_16x16x32_bf16 v[96:99], v[180:183], v[196:199], v[96:99]
	v_mfma_f32_16x16x32_bf16 v[84:87], v[150:153], v[204:207], v[84:87]
	v_mfma_f32_16x16x32_bf16 v[80:83], v[180:183], v[204:207], v[80:83]
	v_mfma_f32_16x16x32_bf16 v[68:71], v[150:153], v[226:229], v[68:71]
	v_mfma_f32_16x16x32_bf16 v[64:67], v[180:183], v[226:229], v[64:67]
	v_mfma_f32_16x16x32_bf16 v[116:119], v[174:177], v[192:195], v[116:119]
	v_mfma_f32_16x16x32_bf16 v[112:115], v[184:187], v[192:195], v[112:115]
	v_mfma_f32_16x16x32_bf16 v[100:103], v[174:177], v[200:203], v[100:103]
	v_mfma_f32_16x16x32_bf16 v[96:99], v[184:187], v[200:203], v[96:99]
	v_mfma_f32_16x16x32_bf16 v[84:87], v[174:177], v[208:211], v[84:87]
	v_mfma_f32_16x16x32_bf16 v[80:83], v[184:187], v[208:211], v[80:83]
	v_mfma_f32_16x16x32_bf16 v[68:71], v[174:177], v[230:233], v[68:71]
	v_mfma_f32_16x16x32_bf16 v[64:67], v[184:187], v[230:233], v[64:67]
	s_barrier
	s_add_i32 s12, s72, s22
	v_lshl_add_u64 v[234:235], v[234:235], 0, s[64:65]
	s_mov_b32 m0, s12
	ds_read_b128 v[188:191], v173 offset:49152
	ds_read_b128 v[192:195], v173 offset:50176
	ds_read_b128 v[196:199], v173 offset:51200
	ds_read_b128 v[200:203], v173 offset:52224
	ds_read_b128 v[204:207], v173 offset:53248
	ds_read_b128 v[208:211], v173 offset:54272
	ds_read_b128 v[226:229], v173 offset:55296
	ds_read_b128 v[230:233], v173 offset:56320
	global_load_lds_dwordx4 v[234:235], off
	s_add_i32 m0, s12, 0x2000
	s_add_u32 s12, s16, 0xb0080
	v_lshl_add_u64 v[234:235], v[236:237], 0, s[64:65]
	s_addc_u32 s13, s17, 0
	s_add_i32 s16, s73, s22
	global_load_lds_dwordx4 v[234:235], off
	v_lshl_add_u64 v[234:235], s[12:13], 0, v[156:157]
	s_mov_b32 m0, s16
	s_nop 0
	global_load_lds_dwordx4 v[234:235], off
	v_lshl_add_u64 v[234:235], s[12:13], 0, v[128:129]
	s_add_i32 m0, s16, 0x2000
	s_nop 0
	global_load_lds_dwordx4 v[234:235], off
	v_lshl_add_u64 v[234:235], v[238:239], 0, s[64:65]
	s_mov_b32 m0, s48
	s_nop 0
	global_load_lds_dwordx4 v[234:235], off
	v_lshl_add_u64 v[234:235], v[240:241], 0, s[64:65]
	s_mov_b32 m0, s49
	s_nop 0
	global_load_lds_dwordx4 v[234:235], off
	s_waitcnt vmcnt(8)
	s_waitcnt lgkmcnt(0)
	s_barrier
	s_waitcnt lgkmcnt(0)
	v_mfma_f32_16x16x32_bf16 v[60:63], v[134:137], v[188:191], v[60:63]
	v_mfma_f32_16x16x32_bf16 v[56:59], v[142:145], v[188:191], v[56:59]
	v_mfma_f32_16x16x32_bf16 v[44:47], v[134:137], v[196:199], v[44:47]
	v_mfma_f32_16x16x32_bf16 v[40:43], v[142:145], v[196:199], v[40:43]
	v_mfma_f32_16x16x32_bf16 v[28:31], v[134:137], v[204:207], v[28:31]
	v_mfma_f32_16x16x32_bf16 v[24:27], v[142:145], v[204:207], v[24:27]
	v_mfma_f32_16x16x32_bf16 v[12:15], v[134:137], v[226:229], v[12:15]
	v_mfma_f32_16x16x32_bf16 v[8:11], v[142:145], v[226:229], v[8:11]
	v_mfma_f32_16x16x32_bf16 v[60:63], v[138:141], v[192:195], v[60:63]
	v_mfma_f32_16x16x32_bf16 v[56:59], v[146:149], v[192:195], v[56:59]
	v_mfma_f32_16x16x32_bf16 v[44:47], v[138:141], v[200:203], v[44:47]
	v_mfma_f32_16x16x32_bf16 v[40:43], v[146:149], v[200:203], v[40:43]
	v_mfma_f32_16x16x32_bf16 v[28:31], v[138:141], v[208:211], v[28:31]
	v_mfma_f32_16x16x32_bf16 v[24:27], v[146:149], v[208:211], v[24:27]
	v_mfma_f32_16x16x32_bf16 v[12:15], v[138:141], v[230:233], v[12:15]
	v_mfma_f32_16x16x32_bf16 v[8:11], v[146:149], v[230:233], v[8:11]
	v_mfma_f32_16x16x32_bf16 v[52:55], v[150:153], v[188:191], v[52:55]
	v_mfma_f32_16x16x32_bf16 v[48:51], v[180:183], v[188:191], v[48:51]
	v_mfma_f32_16x16x32_bf16 v[36:39], v[150:153], v[196:199], v[36:39]
	v_mfma_f32_16x16x32_bf16 v[32:35], v[180:183], v[196:199], v[32:35]
	v_mfma_f32_16x16x32_bf16 v[20:23], v[150:153], v[204:207], v[20:23]
	v_mfma_f32_16x16x32_bf16 v[16:19], v[180:183], v[204:207], v[16:19]
	v_mfma_f32_16x16x32_bf16 v[4:7], v[150:153], v[226:229], v[4:7]
	v_mfma_f32_16x16x32_bf16 v[0:3], v[180:183], v[226:229], v[0:3]
	v_mfma_f32_16x16x32_bf16 v[52:55], v[174:177], v[192:195], v[52:55]
	v_mfma_f32_16x16x32_bf16 v[48:51], v[184:187], v[192:195], v[48:51]
	v_mfma_f32_16x16x32_bf16 v[36:39], v[174:177], v[200:203], v[36:39]
	v_mfma_f32_16x16x32_bf16 v[32:35], v[184:187], v[200:203], v[32:35]
	v_mfma_f32_16x16x32_bf16 v[20:23], v[174:177], v[208:211], v[20:23]
	v_mfma_f32_16x16x32_bf16 v[16:19], v[184:187], v[208:211], v[16:19]
	v_mfma_f32_16x16x32_bf16 v[4:7], v[174:177], v[230:233], v[4:7]
	v_mfma_f32_16x16x32_bf16 v[0:3], v[184:187], v[230:233], v[0:3]
	s_barrier
	s_add_i32 s59, s59, 2
	s_add_u32 s55, s55, 0x100
	s_addc_u32 s58, s58, 0
	s_cmp_gt_u32 s59, 41
	s_mov_b64 s[12:13], s[14:15]
	s_cbranch_scc0 .LBB0_1172
	s_and_b64 vcc, exec, s[8:9]
	s_cbranch_vccz .LBB0_1175
	s_barrier
